# attention loop: softmax VALU order software-pipelined by one pair (exp results consumed 4+ slots later), with static prio
# baseline (speedup 1.0000x reference)
; #define SBAR() __builtin_amdgcn_sched_barrier(0)
; template <int D0> __device__ __forceinline__ void pv_two(f32x16& oa, f32x16& ob, int vb, bf16x8 a0, bf16x8 a1, bf16x8 a2, bf16x8 a3,
;                                                          bf16x8 b0, bf16x8 b1, bf16x8 b2, bf16x8 b3) {
;     ...
;   { const s16x4 l0 = tr_read<v_rd_off(D0, 0, 0)>(vb), h0 = tr_read<v_rd_off(D0, 0, 1)>(vb), l1 = tr_read<v_rd_off(D0, 1, 0)>(vb), h1 = tr_read<v_rd_off(D0, 1, 1)>(vb);
;     asm volatile("s_waitcnt lgkmcnt(0)" ::: "memory"); SBAR();
;     const bf16x8 v0 = PKV(l0, h0), v1 = PKV(l1, h1);
;     oa = MFMA(a0, v0, oa); ob = MFMA(b0, v0, ob); oa = MFMA(a1, v1, oa); ob = MFMA(b1, v1, ob); }
;   { const s16x4 l2 = tr_read<v_rd_off(D0, 2, 0)>(vb), h2 = tr_read<v_rd_off(D0, 2, 1)>(vb), l3 = tr_read<v_rd_off(D0, 3, 0)>(vb), h3 = tr_read<v_rd_off(D0, 3, 1)>(vb);
;     asm volatile("s_waitcnt lgkmcnt(0)" ::: "memory"); SBAR();
;     const bf16x8 v2 = PKV(l2, h2), v3 = PKV(l3, h3);
;     oa = MFMA(a2, v2, oa); ob = MFMA(b2, v2, ob); oa = MFMA(a3, v3, oa); ob = MFMA(b3, v3, ob); }
;     ...
; }
; __device__ __forceinline__ void att_qkt(f32x16& p0, f32x16& p1, const char* Kb, const bf16x8 (&qr)[4], int koff, int ksw, int hi) {
;   p0 = f32x16{}; p1 = f32x16{};
; #pragma unroll
;   for (int d0 = 0; d0 < 4; ++d0) {
;     const int co = ((d0 * 2 + hi) ^ ksw) << 4;
;     const bf16x8 b0 = *(const bf16x8*)(Kb + koff + co);
;     const bf16x8 b1 = *(const bf16x8*)(Kb + koff + 4096 + co);
;     p0 = MFMA(b0, qr[d0], p0); p1 = MFMA(b1, qr[d0], p1);
;   }
; }
; __device__ __forceinline__ void sm_fixed(f32x16& p0, f32x16& p1, float mC, float& l_reg, bf16x8& pa0, bf16x8& pa1, bf16x8& pa2, bf16x8& pa3) {
;   constexpr float C = 1.4426950408889634f;
; #pragma unroll
;   for (int r = 0; r < 16; ++r) p0[r] = __builtin_amdgcn_exp2f(fmaf(p0[r], C, -mC));
; #pragma unroll
;   for (int r = 0; r < 16; ++r) p1[r] = __builtin_amdgcn_exp2f(fmaf(p1[r], C, -mC));
;   float ps = 0;
; #pragma unroll
;   for (int r = 0; r < 16; ++r) ps += p0[r];
; #pragma unroll
;   for (int r = 0; r < 16; ++r) ps += p1[r];
;   { auto rr = __builtin_amdgcn_permlane32_swap(__float_as_uint(ps), __float_as_uint(ps), false, false);
;     ps = __uint_as_float(rr[0]) + __uint_as_float(rr[1]); }
;   l_reg += ps;
;     ...
;   PK4N(p0, 0, pa0); PK4N(p0, 8, pa1); PK4N(p1, 0, pa2); PK4N(p1, 8, pa3);
;     ...
; }
; #pragma unroll
.Lattn_noprio:
	s_waitcnt lgkmcnt(0)
	s_waitcnt vmcnt(4)
	s_barrier
	ds_read_b128 v[240:243], v239 offset:0
	ds_read_b128 v[244:247], v238 offset:0
	ds_read_b128 v[218:221], v237 offset:0
	ds_read_b128 v[210:213], v235 offset:0
	s_waitcnt lgkmcnt(3)
	v_mfma_f32_32x32x16_bf16 v[128:143], v[240:243], v[180:183], 0
	ds_read_b128 v[240:243], v239 offset:4096
	s_add_u32 m0, s7, 0x8000
	s_nop 0
	global_load_lds_dwordx4 v248, s[40:41]
	s_waitcnt lgkmcnt(3)
	v_mfma_f32_32x32x16_bf16 v[128:143], v[244:247], v[176:179], v[128:143]
	ds_read_b128 v[244:247], v238 offset:4096
	s_add_u32 m0, s7, 0xa000
	s_add_u32 s18, s40, 0x80
	s_addc_u32 s19, s41, 0
	global_load_lds_dwordx4 v248, s[18:19]
	s_waitcnt lgkmcnt(3)
	v_mfma_f32_32x32x16_bf16 v[128:143], v[218:221], v[172:175], v[128:143]
	ds_read_b128 v[218:221], v237 offset:4096
	s_add_u32 m0, s7, 0x9000
	s_add_u32 s18, s40, 0x2c000
	s_addc_u32 s19, s41, 0
	global_load_lds_dwordx4 v248, s[18:19]
	s_waitcnt lgkmcnt(3)
	v_mfma_f32_32x32x16_bf16 v[128:143], v[210:213], v[168:171], v[128:143]
	ds_read_b128 v[210:213], v235 offset:4096
	s_add_u32 m0, s7, 0xb000
	s_add_u32 s18, s40, 0x2c080
	s_addc_u32 s19, s41, 0
	global_load_lds_dwordx4 v248, s[18:19]
	s_add_u32 s40, s40, 0x58000
	s_addc_u32 s41, s41, 0
	s_waitcnt lgkmcnt(3)
	v_mfma_f32_32x32x16_bf16 v[144:159], v[240:243], v[180:183], 0
	ds_read_b128 v[240:243], v239 offset:8192
	s_nop 1
	v_fmamk_f32 v128, v128, 0x3fb8aa3b, v233
	v_fmamk_f32 v129, v129, 0x3fb8aa3b, v233
	v_exp_f32_e32 v128, v128
	v_exp_f32_e32 v129, v129
	v_fmamk_f32 v130, v130, 0x3fb8aa3b, v233
	v_fmamk_f32 v131, v131, 0x3fb8aa3b, v233
	v_exp_f32_e32 v130, v130
	v_exp_f32_e32 v131, v131
	v_add_f32_e32 v204, v204, v128
	v_add_f32_e32 v204, v204, v129
	v_cvt_pk_bf16_f32 v184, v128, v129
	v_fmamk_f32 v132, v132, 0x3fb8aa3b, v233
	v_fmamk_f32 v133, v133, 0x3fb8aa3b, v233
	v_exp_f32_e32 v132, v132
	s_waitcnt lgkmcnt(3)
	v_mfma_f32_32x32x16_bf16 v[144:159], v[244:247], v[176:179], v[144:159]
	ds_read_b128 v[244:247], v238 offset:8192
	v_exp_f32_e32 v133, v133
	v_add_f32_e32 v204, v204, v130
	v_add_f32_e32 v204, v204, v131
	v_cvt_pk_bf16_f32 v185, v130, v131
	v_fmamk_f32 v134, v134, 0x3fb8aa3b, v233
	v_fmamk_f32 v135, v135, 0x3fb8aa3b, v233
	v_exp_f32_e32 v134, v134
	v_exp_f32_e32 v135, v135
	v_add_f32_e32 v204, v204, v132
	v_add_f32_e32 v204, v204, v133
	v_cvt_pk_bf16_f32 v186, v132, v133
	v_fmamk_f32 v136, v136, 0x3fb8aa3b, v233
	v_fmamk_f32 v137, v137, 0x3fb8aa3b, v233
	v_exp_f32_e32 v136, v136
	s_waitcnt lgkmcnt(3)
	v_mfma_f32_32x32x16_bf16 v[144:159], v[218:221], v[172:175], v[144:159]
	ds_read_b128 v[218:221], v237 offset:8192
	v_exp_f32_e32 v137, v137
	v_add_f32_e32 v204, v204, v134
	v_add_f32_e32 v204, v204, v135
	v_cvt_pk_bf16_f32 v187, v134, v135
	v_fmamk_f32 v138, v138, 0x3fb8aa3b, v233
	v_fmamk_f32 v139, v139, 0x3fb8aa3b, v233
	v_exp_f32_e32 v138, v138
	v_exp_f32_e32 v139, v139
	v_add_f32_e32 v204, v204, v136
	v_add_f32_e32 v204, v204, v137
	v_cvt_pk_bf16_f32 v188, v136, v137
	v_fmamk_f32 v140, v140, 0x3fb8aa3b, v233
	v_fmamk_f32 v141, v141, 0x3fb8aa3b, v233
	v_exp_f32_e32 v140, v140
	s_waitcnt lgkmcnt(3)
	v_mfma_f32_32x32x16_bf16 v[144:159], v[210:213], v[168:171], v[144:159]
	ds_read_b128 v[210:213], v230 offset:0
	v_exp_f32_e32 v141, v141
	v_add_f32_e32 v204, v204, v138
	v_add_f32_e32 v204, v204, v139
	v_cvt_pk_bf16_f32 v189, v138, v139
	v_fmamk_f32 v142, v142, 0x3fb8aa3b, v233
	v_fmamk_f32 v143, v143, 0x3fb8aa3b, v233
	v_exp_f32_e32 v142, v142
	v_exp_f32_e32 v143, v143
	v_add_f32_e32 v204, v204, v140
	v_add_f32_e32 v204, v204, v141
	v_cvt_pk_bf16_f32 v190, v140, v141
	v_add_f32_e32 v204, v204, v142
	v_add_f32_e32 v204, v204, v143
	v_cvt_pk_bf16_f32 v191, v142, v143
.Lattn_loop:
	s_waitcnt vmcnt(4)
	s_barrier
	s_waitcnt lgkmcnt(3)
	v_mfma_f32_32x32x16_bf16 v[128:143], v[240:243], v[164:167], 0
	ds_read_b128 v[240:243], v235 offset:8192
	v_fmamk_f32 v144, v144, 0x3fb8aa3b, v233
	v_fmamk_f32 v145, v145, 0x3fb8aa3b, v233
	v_exp_f32_e32 v144, v144
	v_exp_f32_e32 v145, v145
	v_fmamk_f32 v146, v146, 0x3fb8aa3b, v233
	s_add_u32 m0, s7, 0xc000
	s_nop 0
	global_load_lds_dwordx4 v249, s[98:99]
	s_waitcnt lgkmcnt(3)
	v_mfma_f32_32x32x16_bf16 v[128:143], v[244:247], v[160:163], v[128:143]
	ds_read_b128 v[244:247], v230 offset:4096
	v_fmamk_f32 v147, v147, 0x3fb8aa3b, v233
	v_exp_f32_e32 v146, v146
	v_exp_f32_e32 v147, v147
	v_add_f32_e32 v204, v204, v144
	v_add_f32_e32 v204, v204, v145
	s_add_u32 m0, s7, 0xd000
	s_add_u32 s18, s98, 0x16000
	s_addc_u32 s19, s99, 0
	global_load_lds_dwordx4 v249, s[18:19]
	s_waitcnt lgkmcnt(2)
	v_mfma_f32_32x32x16_bf16 v[128:143], v[218:221], v[210:213], v[128:143]
	ds_read_b64_tr_b16 v[218:219], v234 offset:0
	ds_read_b64_tr_b16 v[220:221], v234 offset:2048
	ds_read_b64_tr_b16 v[210:211], v234 offset:512
	ds_read_b64_tr_b16 v[212:213], v234 offset:2560
	v_cvt_pk_bf16_f32 v192, v144, v145
	v_fmamk_f32 v148, v148, 0x3fb8aa3b, v233
	v_fmamk_f32 v149, v149, 0x3fb8aa3b, v233
	v_exp_f32_e32 v148, v148
	v_exp_f32_e32 v149, v149
	s_add_u32 m0, s7, 0xe000
	s_add_u32 s18, s98, 0x2c000
	s_addc_u32 s19, s99, 0
	global_load_lds_dwordx4 v249, s[18:19]
	s_waitcnt lgkmcnt(4)
	v_mfma_f32_32x32x16_bf16 v[128:143], v[240:243], v[244:247], v[128:143]
	ds_read_b64_tr_b16 v[240:241], v234 offset:1024
	ds_read_b64_tr_b16 v[242:243], v234 offset:3072
	ds_read_b64_tr_b16 v[244:245], v234 offset:1536
	ds_read_b64_tr_b16 v[246:247], v234 offset:3584
	v_add_f32_e32 v204, v204, v146
	v_add_f32_e32 v204, v204, v147
	v_cvt_pk_bf16_f32 v193, v146, v147
	v_fmamk_f32 v150, v150, 0x3fb8aa3b, v233
	v_fmamk_f32 v151, v151, 0x3fb8aa3b, v233
	s_add_u32 m0, s7, 0xf000
	s_add_u32 s18, s98, 0x42000
	s_addc_u32 s19, s99, 0
	global_load_lds_dwordx4 v249, s[18:19]
	s_add_u32 s98, s98, 0x58000
	s_addc_u32 s99, s99, 0
	s_waitcnt lgkmcnt(6)
; #define SBAR() __builtin_amdgcn_sched_barrier(0)
; template <int D0> __device__ __forceinline__ void pv_two(f32x16& oa, f32x16& ob, int vb, bf16x8 a0, bf16x8 a1, bf16x8 a2, bf16x8 a3,
;                                                          bf16x8 b0, bf16x8 b1, bf16x8 b2, bf16x8 b3) {
;     ...
;   { const s16x4 l0 = tr_read<v_rd_off(D0, 0, 0)>(vb), h0 = tr_read<v_rd_off(D0, 0, 1)>(vb), l1 = tr_read<v_rd_off(D0, 1, 0)>(vb), h1 = tr_read<v_rd_off(D0, 1, 1)>(vb);
;     asm volatile("s_waitcnt lgkmcnt(0)" ::: "memory"); SBAR();
;     const bf16x8 v0 = PKV(l0, h0), v1 = PKV(l1, h1);
;     oa = MFMA(a0, v0, oa); ob = MFMA(b0, v0, ob); oa = MFMA(a1, v1, oa); ob = MFMA(b1, v1, ob); }
;   { const s16x4 l2 = tr_read<v_rd_off(D0, 2, 0)>(vb), h2 = tr_read<v_rd_off(D0, 2, 1)>(vb), l3 = tr_read<v_rd_off(D0, 3, 0)>(vb), h3 = tr_read<v_rd_off(D0, 3, 1)>(vb);
;     asm volatile("s_waitcnt lgkmcnt(0)" ::: "memory"); SBAR();
;     const bf16x8 v2 = PKV(l2, h2), v3 = PKV(l3, h3);
;     oa = MFMA(a2, v2, oa); ob = MFMA(b2, v2, ob); oa = MFMA(a3, v3, oa); ob = MFMA(b3, v3, ob); }
;     ...
; }
; __device__ __forceinline__ void att_qkt(f32x16& p0, f32x16& p1, const char* Kb, const bf16x8 (&qr)[4], int koff, int ksw, int hi) {
;   p0 = f32x16{}; p1 = f32x16{};
; #pragma unroll
;   for (int d0 = 0; d0 < 4; ++d0) {
;     const int co = ((d0 * 2 + hi) ^ ksw) << 4;
;     const bf16x8 b0 = *(const bf16x8*)(Kb + koff + co);
;     const bf16x8 b1 = *(const bf16x8*)(Kb + koff + 4096 + co);
;     p0 = MFMA(b0, qr[d0], p0); p1 = MFMA(b1, qr[d0], p1);
;   }
; }
; __device__ __forceinline__ void sm_fixed(f32x16& p0, f32x16& p1, float mC, float& l_reg, bf16x8& pa0, bf16x8& pa1, bf16x8& pa2, bf16x8& pa3) {
;   constexpr float C = 1.4426950408889634f;
; #pragma unroll
;   for (int r = 0; r < 16; ++r) p0[r] = __builtin_amdgcn_exp2f(fmaf(p0[r], C, -mC));
; #pragma unroll
;   for (int r = 0; r < 16; ++r) p1[r] = __builtin_amdgcn_exp2f(fmaf(p1[r], C, -mC));
;   float ps = 0;
; #pragma unroll
;   for (int r = 0; r < 16; ++r) ps += p0[r];
; #pragma unroll
;   for (int r = 0; r < 16; ++r) ps += p1[r];
;   { auto rr = __builtin_amdgcn_permlane32_swap(__float_as_uint(ps), __float_as_uint(ps), false, false);
;     ps = __uint_as_float(rr[0]) + __uint_as_float(rr[1]); }
;   l_reg += ps;
;     ...
;   PK4N(p0, 0, pa0); PK4N(p0, 8, pa1); PK4N(p1, 0, pa2); PK4N(p1, 8, pa3);
;     ...
; }
; #pragma unroll
	v_mfma_f32_32x32x16_bf16 v[64:79], v[184:187], v[218:221], v[64:79]
	ds_read_b64_tr_b16 v[218:219], v234 offset:4096
	ds_read_b64_tr_b16 v[220:221], v234 offset:6144
	v_exp_f32_e32 v150, v150
	v_exp_f32_e32 v151, v151
	v_add_f32_e32 v204, v204, v148
	v_add_f32_e32 v204, v204, v149
	v_cvt_pk_bf16_f32 v194, v148, v149
	s_waitcnt lgkmcnt(6)
	v_mfma_f32_32x32x16_bf16 v[80:95], v[184:187], v[210:213], v[80:95]
	ds_read_b64_tr_b16 v[210:211], v234 offset:4608
	ds_read_b64_tr_b16 v[212:213], v234 offset:6656
	v_fmamk_f32 v152, v152, 0x3fb8aa3b, v233
	v_fmamk_f32 v153, v153, 0x3fb8aa3b, v233
	v_exp_f32_e32 v152, v152
	v_exp_f32_e32 v153, v153
	v_add_f32_e32 v204, v204, v150
	s_waitcnt lgkmcnt(6)
	v_mfma_f32_32x32x16_bf16 v[96:111], v[184:187], v[240:243], v[96:111]
	ds_read_b64_tr_b16 v[240:241], v234 offset:5120
	ds_read_b64_tr_b16 v[242:243], v234 offset:7168
	v_add_f32_e32 v204, v204, v151
	v_cvt_pk_bf16_f32 v195, v150, v151
	v_fmamk_f32 v154, v154, 0x3fb8aa3b, v233
	v_fmamk_f32 v155, v155, 0x3fb8aa3b, v233
	v_exp_f32_e32 v154, v154
	s_waitcnt lgkmcnt(6)
	v_mfma_f32_32x32x16_bf16 v[112:127], v[184:187], v[244:247], v[112:127]
	ds_read_b64_tr_b16 v[244:245], v234 offset:5632
	ds_read_b64_tr_b16 v[246:247], v234 offset:7680
	v_exp_f32_e32 v155, v155
	v_add_f32_e32 v204, v204, v152
	v_add_f32_e32 v204, v204, v153
	v_cvt_pk_bf16_f32 v196, v152, v153
	v_fmamk_f32 v156, v156, 0x3fb8aa3b, v233
	s_waitcnt lgkmcnt(6)
	v_mfma_f32_32x32x16_bf16 v[64:79], v[188:191], v[218:221], v[64:79]
	ds_read_b64_tr_b16 v[218:219], v234 offset:8192
	ds_read_b64_tr_b16 v[220:221], v234 offset:10240
	v_fmamk_f32 v157, v157, 0x3fb8aa3b, v233
	v_exp_f32_e32 v156, v156
	v_exp_f32_e32 v157, v157
	v_add_f32_e32 v204, v204, v154
	s_waitcnt lgkmcnt(6)
	v_mfma_f32_32x32x16_bf16 v[80:95], v[188:191], v[210:213], v[80:95]
	ds_read_b64_tr_b16 v[210:211], v234 offset:8704
	ds_read_b64_tr_b16 v[212:213], v234 offset:10752
	v_add_f32_e32 v204, v204, v155
	v_cvt_pk_bf16_f32 v197, v154, v155
	v_fmamk_f32 v158, v158, 0x3fb8aa3b, v233
	v_fmamk_f32 v159, v159, 0x3fb8aa3b, v233
	s_waitcnt lgkmcnt(6)
	v_mfma_f32_32x32x16_bf16 v[96:111], v[188:191], v[240:243], v[96:111]
	ds_read_b64_tr_b16 v[240:241], v234 offset:9216
	ds_read_b64_tr_b16 v[242:243], v234 offset:11264
	v_exp_f32_e32 v158, v158
	v_exp_f32_e32 v159, v159
	v_add_f32_e32 v204, v204, v156
	v_add_f32_e32 v204, v204, v157
	s_waitcnt lgkmcnt(6)
	v_mfma_f32_32x32x16_bf16 v[112:127], v[188:191], v[244:247], v[112:127]
	ds_read_b64_tr_b16 v[244:245], v234 offset:9728
	ds_read_b64_tr_b16 v[246:247], v234 offset:11776
	v_cvt_pk_bf16_f32 v198, v156, v157
	v_add_f32_e32 v204, v204, v158
	v_add_f32_e32 v204, v204, v159
	v_cvt_pk_bf16_f32 v199, v158, v159
	s_waitcnt lgkmcnt(6)
	v_mfma_f32_32x32x16_bf16 v[64:79], v[192:195], v[218:221], v[64:79]
	ds_read_b128 v[218:221], v239 offset:12288
	v_fmamk_f32 v128, v128, 0x3fb8aa3b, v231
	v_fmamk_f32 v129, v129, 0x3fb8aa3b, v231
	v_exp_f32_e32 v128, v128
	v_exp_f32_e32 v129, v129
	v_fmamk_f32 v130, v130, 0x3fb8aa3b, v231
	s_waitcnt lgkmcnt(5)
	v_mfma_f32_32x32x16_bf16 v[80:95], v[192:195], v[210:213], v[80:95]
	ds_read_b128 v[210:213], v238 offset:12288
	v_fmamk_f32 v131, v131, 0x3fb8aa3b, v231
	v_exp_f32_e32 v130, v130
	v_exp_f32_e32 v131, v131
	v_add_f32_e32 v205, v205, v128
	v_add_f32_e32 v205, v205, v129
	s_waitcnt lgkmcnt(4)
	v_mfma_f32_32x32x16_bf16 v[96:111], v[192:195], v[240:243], v[96:111]
	ds_read_b128 v[240:243], v237 offset:12288
	v_cvt_pk_bf16_f32 v184, v128, v129
	v_fmamk_f32 v132, v132, 0x3fb8aa3b, v231
	v_fmamk_f32 v133, v133, 0x3fb8aa3b, v231
	v_exp_f32_e32 v132, v132
	v_exp_f32_e32 v133, v133
	s_waitcnt lgkmcnt(3)
	v_mfma_f32_32x32x16_bf16 v[112:127], v[192:195], v[244:247], v[112:127]
	ds_read_b128 v[244:247], v230 offset:0
	v_add_f32_e32 v205, v205, v130
	v_add_f32_e32 v205, v205, v131
	v_cvt_pk_bf16_f32 v185, v130, v131
	v_fmamk_f32 v134, v134, 0x3fb8aa3b, v231
	v_fmamk_f32 v135, v135, 0x3fb8aa3b, v231
	s_waitcnt lgkmcnt(3)
	v_mfma_f32_32x32x16_bf16 v[144:159], v[218:221], v[164:167], 0
	ds_read_b128 v[218:221], v235 offset:12288
	v_exp_f32_e32 v134, v134
	v_exp_f32_e32 v135, v135
	v_add_f32_e32 v205, v205, v132
	v_add_f32_e32 v205, v205, v133
	v_cvt_pk_bf16_f32 v186, v132, v133
	s_waitcnt lgkmcnt(3)
	v_mfma_f32_32x32x16_bf16 v[144:159], v[210:213], v[160:163], v[144:159]
	ds_read_b128 v[210:213], v230 offset:4096
	v_fmamk_f32 v136, v136, 0x3fb8aa3b, v231
	v_fmamk_f32 v137, v137, 0x3fb8aa3b, v231
	v_exp_f32_e32 v136, v136
	v_exp_f32_e32 v137, v137
	v_add_f32_e32 v205, v205, v134
	s_waitcnt lgkmcnt(2)
	v_mfma_f32_32x32x16_bf16 v[144:159], v[240:243], v[244:247], v[144:159]
	ds_read_b64_tr_b16 v[240:241], v234 offset:12288
	ds_read_b64_tr_b16 v[242:243], v234 offset:14336
	ds_read_b64_tr_b16 v[244:245], v234 offset:12800
	ds_read_b64_tr_b16 v[246:247], v234 offset:14848
	v_add_f32_e32 v205, v205, v135
	v_cvt_pk_bf16_f32 v187, v134, v135
	v_fmamk_f32 v138, v138, 0x3fb8aa3b, v231
	v_fmamk_f32 v139, v139, 0x3fb8aa3b, v231
	v_exp_f32_e32 v138, v138
	s_waitcnt lgkmcnt(4)
	v_mfma_f32_32x32x16_bf16 v[144:159], v[218:221], v[210:213], v[144:159]
	ds_read_b64_tr_b16 v[218:219], v234 offset:13312
	ds_read_b64_tr_b16 v[220:221], v234 offset:15360
	ds_read_b64_tr_b16 v[210:211], v234 offset:13824
	ds_read_b64_tr_b16 v[212:213], v234 offset:15872
	v_exp_f32_e32 v139, v139
	v_add_f32_e32 v205, v205, v136
	v_add_f32_e32 v205, v205, v137
	v_cvt_pk_bf16_f32 v188, v136, v137
	v_fmamk_f32 v140, v140, 0x3fb8aa3b, v231
	s_waitcnt lgkmcnt(6)
	v_mfma_f32_32x32x16_bf16 v[64:79], v[196:199], v[240:243], v[64:79]
	ds_read_b64_tr_b16 v[240:241], v234 offset:0
	ds_read_b64_tr_b16 v[242:243], v234 offset:2048
	v_fmamk_f32 v141, v141, 0x3fb8aa3b, v231
	v_exp_f32_e32 v140, v140
	v_exp_f32_e32 v141, v141
	v_add_f32_e32 v205, v205, v138
	s_waitcnt lgkmcnt(6)
	v_mfma_f32_32x32x16_bf16 v[80:95], v[196:199], v[244:247], v[80:95]
	ds_read_b64_tr_b16 v[244:245], v234 offset:512
	ds_read_b64_tr_b16 v[246:247], v234 offset:2560
	v_add_f32_e32 v205, v205, v139
	v_cvt_pk_bf16_f32 v189, v138, v139
	v_fmamk_f32 v142, v142, 0x3fb8aa3b, v231
	v_fmamk_f32 v143, v143, 0x3fb8aa3b, v231
	s_waitcnt lgkmcnt(6)
	v_mfma_f32_32x32x16_bf16 v[96:111], v[196:199], v[218:221], v[96:111]
	ds_read_b64_tr_b16 v[218:219], v234 offset:1024
	ds_read_b64_tr_b16 v[220:221], v234 offset:3072
	v_exp_f32_e32 v142, v142
	v_exp_f32_e32 v143, v143
	v_add_f32_e32 v205, v205, v140
	v_add_f32_e32 v205, v205, v141
	s_waitcnt lgkmcnt(6)
	v_mfma_f32_32x32x16_bf16 v[112:127], v[196:199], v[210:213], v[112:127]
	ds_read_b64_tr_b16 v[210:211], v234 offset:1536
	ds_read_b64_tr_b16 v[212:213], v234 offset:3584
	v_cvt_pk_bf16_f32 v190, v140, v141
	v_add_f32_e32 v205, v205, v142
	v_add_f32_e32 v205, v205, v143
	v_cvt_pk_bf16_f32 v191, v142, v143
	s_add_i32 s6, s6, -1
	s_cmp_eq_u32 s6, 0
	s_cbranch_scc1 .Lattn_exit
; #define SBAR() __builtin_amdgcn_sched_barrier(0)
; template <int D0> __device__ __forceinline__ void pv_two(f32x16& oa, f32x16& ob, int vb, bf16x8 a0, bf16x8 a1, bf16x8 a2, bf16x8 a3,
;                                                          bf16x8 b0, bf16x8 b1, bf16x8 b2, bf16x8 b3) {
;     ...
;   { const s16x4 l0 = tr_read<v_rd_off(D0, 0, 0)>(vb), h0 = tr_read<v_rd_off(D0, 0, 1)>(vb), l1 = tr_read<v_rd_off(D0, 1, 0)>(vb), h1 = tr_read<v_rd_off(D0, 1, 1)>(vb);
;     asm volatile("s_waitcnt lgkmcnt(0)" ::: "memory"); SBAR();
;     const bf16x8 v0 = PKV(l0, h0), v1 = PKV(l1, h1);
;     oa = MFMA(a0, v0, oa); ob = MFMA(b0, v0, ob); oa = MFMA(a1, v1, oa); ob = MFMA(b1, v1, ob); }
;   { const s16x4 l2 = tr_read<v_rd_off(D0, 2, 0)>(vb), h2 = tr_read<v_rd_off(D0, 2, 1)>(vb), l3 = tr_read<v_rd_off(D0, 3, 0)>(vb), h3 = tr_read<v_rd_off(D0, 3, 1)>(vb);
;     asm volatile("s_waitcnt lgkmcnt(0)" ::: "memory"); SBAR();
;     const bf16x8 v2 = PKV(l2, h2), v3 = PKV(l3, h3);
;     oa = MFMA(a2, v2, oa); ob = MFMA(b2, v2, ob); oa = MFMA(a3, v3, oa); ob = MFMA(b3, v3, ob); }
;     ...
; }
; __device__ __forceinline__ void att_qkt(f32x16& p0, f32x16& p1, const char* Kb, const bf16x8 (&qr)[4], int koff, int ksw, int hi) {
;   p0 = f32x16{}; p1 = f32x16{};
; #pragma unroll
;   for (int d0 = 0; d0 < 4; ++d0) {
;     const int co = ((d0 * 2 + hi) ^ ksw) << 4;
;     const bf16x8 b0 = *(const bf16x8*)(Kb + koff + co);
;     const bf16x8 b1 = *(const bf16x8*)(Kb + koff + 4096 + co);
;     p0 = MFMA(b0, qr[d0], p0); p1 = MFMA(b1, qr[d0], p1);
;   }
; }
; __device__ __forceinline__ void sm_fixed(f32x16& p0, f32x16& p1, float mC, float& l_reg, bf16x8& pa0, bf16x8& pa1, bf16x8& pa2, bf16x8& pa3) {
;   constexpr float C = 1.4426950408889634f;
; #pragma unroll
;   for (int r = 0; r < 16; ++r) p0[r] = __builtin_amdgcn_exp2f(fmaf(p0[r], C, -mC));
; #pragma unroll
;   for (int r = 0; r < 16; ++r) p1[r] = __builtin_amdgcn_exp2f(fmaf(p1[r], C, -mC));
;   float ps = 0;
; #pragma unroll
;   for (int r = 0; r < 16; ++r) ps += p0[r];
; #pragma unroll
;   for (int r = 0; r < 16; ++r) ps += p1[r];
;   { auto rr = __builtin_amdgcn_permlane32_swap(__float_as_uint(ps), __float_as_uint(ps), false, false);
;     ps = __uint_as_float(rr[0]) + __uint_as_float(rr[1]); }
;   l_reg += ps;
;     ...
;   PK4N(p0, 0, pa0); PK4N(p0, 8, pa1); PK4N(p1, 0, pa2); PK4N(p1, 8, pa3);
;     ...
; }
; #pragma unroll
	s_waitcnt vmcnt(4)
	s_barrier
	s_waitcnt lgkmcnt(6)
	v_mfma_f32_32x32x16_bf16 v[0:15], v[184:187], v[240:243], v[0:15]
	ds_read_b128 v[240:243], v239 offset:32768
	v_fmamk_f32 v144, v144, 0x3fb8aa3b, v231
	v_fmamk_f32 v145, v145, 0x3fb8aa3b, v231
	v_exp_f32_e32 v144, v144
	v_exp_f32_e32 v145, v145
	v_fmamk_f32 v146, v146, 0x3fb8aa3b, v231
	s_add_u32 m0, s7, 0x0
	s_nop 0
	global_load_lds_dwordx4 v248, s[40:41]
	s_waitcnt lgkmcnt(5)
	v_mfma_f32_32x32x16_bf16 v[16:31], v[184:187], v[244:247], v[16:31]
	ds_read_b128 v[244:247], v238 offset:32768
	v_fmamk_f32 v147, v147, 0x3fb8aa3b, v231
	v_exp_f32_e32 v146, v146
	v_exp_f32_e32 v147, v147
	v_add_f32_e32 v205, v205, v144
	v_add_f32_e32 v205, v205, v145
	s_add_u32 m0, s7, 0x2000
	s_add_u32 s18, s40, 0x80
	s_addc_u32 s19, s41, 0
	global_load_lds_dwordx4 v248, s[18:19]
	s_waitcnt lgkmcnt(4)
	v_mfma_f32_32x32x16_bf16 v[32:47], v[184:187], v[218:221], v[32:47]
	ds_read_b128 v[218:221], v237 offset:32768
	v_cvt_pk_bf16_f32 v192, v144, v145
	v_fmamk_f32 v148, v148, 0x3fb8aa3b, v231
	v_fmamk_f32 v149, v149, 0x3fb8aa3b, v231
	v_exp_f32_e32 v148, v148
	v_exp_f32_e32 v149, v149
	s_add_u32 m0, s7, 0x1000
	s_add_u32 s18, s40, 0x2c000
	s_addc_u32 s19, s41, 0
	global_load_lds_dwordx4 v248, s[18:19]
	s_waitcnt lgkmcnt(3)
	v_mfma_f32_32x32x16_bf16 v[48:63], v[184:187], v[210:213], v[48:63]
	ds_read_b128 v[210:213], v235 offset:32768
	v_add_f32_e32 v205, v205, v146
	v_add_f32_e32 v205, v205, v147
	v_cvt_pk_bf16_f32 v193, v146, v147
	v_fmamk_f32 v150, v150, 0x3fb8aa3b, v231
	v_fmamk_f32 v151, v151, 0x3fb8aa3b, v231
	s_add_u32 m0, s7, 0x3000
	s_add_u32 s18, s40, 0x2c080
	s_addc_u32 s19, s41, 0
	global_load_lds_dwordx4 v248, s[18:19]
	s_add_u32 s40, s40, 0x58000
	s_addc_u32 s41, s41, 0
	s_waitcnt lgkmcnt(3)
	v_mfma_f32_32x32x16_bf16 v[128:143], v[240:243], v[180:183], 0
	ds_read_b64_tr_b16 v[240:241], v234 offset:4096
	ds_read_b64_tr_b16 v[242:243], v234 offset:6144
	v_exp_f32_e32 v150, v150
	v_exp_f32_e32 v151, v151
	v_add_f32_e32 v205, v205, v148
	v_add_f32_e32 v205, v205, v149
	v_cvt_pk_bf16_f32 v194, v148, v149
	s_waitcnt lgkmcnt(4)
	v_mfma_f32_32x32x16_bf16 v[128:143], v[244:247], v[176:179], v[128:143]
	ds_read_b64_tr_b16 v[244:245], v234 offset:4608
	ds_read_b64_tr_b16 v[246:247], v234 offset:6656
	v_fmamk_f32 v152, v152, 0x3fb8aa3b, v231
	v_fmamk_f32 v153, v153, 0x3fb8aa3b, v231
	v_exp_f32_e32 v152, v152
	v_exp_f32_e32 v153, v153
	v_add_f32_e32 v205, v205, v150
	s_waitcnt lgkmcnt(5)
	v_mfma_f32_32x32x16_bf16 v[128:143], v[218:221], v[172:175], v[128:143]
	ds_read_b64_tr_b16 v[218:219], v234 offset:5120
	ds_read_b64_tr_b16 v[220:221], v234 offset:7168
	v_add_f32_e32 v205, v205, v151
	v_cvt_pk_bf16_f32 v195, v150, v151
	v_fmamk_f32 v154, v154, 0x3fb8aa3b, v231
	v_fmamk_f32 v155, v155, 0x3fb8aa3b, v231
	v_exp_f32_e32 v154, v154
	s_waitcnt lgkmcnt(6)
	v_mfma_f32_32x32x16_bf16 v[128:143], v[210:213], v[168:171], v[128:143]
	ds_read_b64_tr_b16 v[210:211], v234 offset:5632
	ds_read_b64_tr_b16 v[212:213], v234 offset:7680
	v_exp_f32_e32 v155, v155
	v_add_f32_e32 v205, v205, v152
	v_add_f32_e32 v205, v205, v153
	v_cvt_pk_bf16_f32 v196, v152, v153
	v_fmamk_f32 v156, v156, 0x3fb8aa3b, v231
	s_waitcnt lgkmcnt(6)
	v_mfma_f32_32x32x16_bf16 v[0:15], v[188:191], v[240:243], v[0:15]
	ds_read_b64_tr_b16 v[240:241], v234 offset:8192
	ds_read_b64_tr_b16 v[242:243], v234 offset:10240
	v_fmamk_f32 v157, v157, 0x3fb8aa3b, v231
	v_exp_f32_e32 v156, v156
	v_exp_f32_e32 v157, v157
	v_add_f32_e32 v205, v205, v154
	s_waitcnt lgkmcnt(6)
	v_mfma_f32_32x32x16_bf16 v[16:31], v[188:191], v[244:247], v[16:31]
	ds_read_b64_tr_b16 v[244:245], v234 offset:8704
	ds_read_b64_tr_b16 v[246:247], v234 offset:10752
	v_add_f32_e32 v205, v205, v155
	v_cvt_pk_bf16_f32 v197, v154, v155
	v_fmamk_f32 v158, v158, 0x3fb8aa3b, v231
	v_fmamk_f32 v159, v159, 0x3fb8aa3b, v231
	s_waitcnt lgkmcnt(6)
	v_mfma_f32_32x32x16_bf16 v[32:47], v[188:191], v[218:221], v[32:47]
	ds_read_b64_tr_b16 v[218:219], v234 offset:9216
	ds_read_b64_tr_b16 v[220:221], v234 offset:11264
	v_exp_f32_e32 v158, v158
	v_exp_f32_e32 v159, v159
	v_add_f32_e32 v205, v205, v156
	v_add_f32_e32 v205, v205, v157
	s_waitcnt lgkmcnt(6)
	v_mfma_f32_32x32x16_bf16 v[48:63], v[188:191], v[210:213], v[48:63]
	ds_read_b64_tr_b16 v[210:211], v234 offset:9728
	ds_read_b64_tr_b16 v[212:213], v234 offset:11776
	v_cvt_pk_bf16_f32 v198, v156, v157
	v_add_f32_e32 v205, v205, v158
	v_add_f32_e32 v205, v205, v159
	v_cvt_pk_bf16_f32 v199, v158, v159
	s_waitcnt lgkmcnt(6)
	v_mfma_f32_32x32x16_bf16 v[0:15], v[192:195], v[240:243], v[0:15]
	ds_read_b128 v[240:243], v239 offset:36864
	v_fmamk_f32 v128, v128, 0x3fb8aa3b, v233
	v_fmamk_f32 v129, v129, 0x3fb8aa3b, v233
	v_exp_f32_e32 v128, v128
	v_exp_f32_e32 v129, v129
	v_fmamk_f32 v130, v130, 0x3fb8aa3b, v233
	s_waitcnt lgkmcnt(5)
	v_mfma_f32_32x32x16_bf16 v[16:31], v[192:195], v[244:247], v[16:31]
	ds_read_b128 v[244:247], v238 offset:36864
	v_fmamk_f32 v131, v131, 0x3fb8aa3b, v233
	v_exp_f32_e32 v130, v130
	v_exp_f32_e32 v131, v131
	v_add_f32_e32 v204, v204, v128
	v_add_f32_e32 v204, v204, v129
	s_waitcnt lgkmcnt(4)
	v_mfma_f32_32x32x16_bf16 v[32:47], v[192:195], v[218:221], v[32:47]
	ds_read_b128 v[218:221], v237 offset:36864
	v_cvt_pk_bf16_f32 v184, v128, v129
	v_fmamk_f32 v132, v132, 0x3fb8aa3b, v233
	v_fmamk_f32 v133, v133, 0x3fb8aa3b, v233
	v_exp_f32_e32 v132, v132
	v_exp_f32_e32 v133, v133
	s_waitcnt lgkmcnt(3)
	v_mfma_f32_32x32x16_bf16 v[48:63], v[192:195], v[210:213], v[48:63]
	ds_read_b128 v[210:213], v235 offset:36864
	v_add_f32_e32 v204, v204, v130
	v_add_f32_e32 v204, v204, v131
	v_cvt_pk_bf16_f32 v185, v130, v131
	v_fmamk_f32 v134, v134, 0x3fb8aa3b, v233
	v_fmamk_f32 v135, v135, 0x3fb8aa3b, v233
	s_waitcnt lgkmcnt(3)
; #define SBAR() __builtin_amdgcn_sched_barrier(0)
; template <int D0> __device__ __forceinline__ void pv_two(f32x16& oa, f32x16& ob, int vb, bf16x8 a0, bf16x8 a1, bf16x8 a2, bf16x8 a3,
;                                                          bf16x8 b0, bf16x8 b1, bf16x8 b2, bf16x8 b3) {
;     ...
;   { const s16x4 l0 = tr_read<v_rd_off(D0, 0, 0)>(vb), h0 = tr_read<v_rd_off(D0, 0, 1)>(vb), l1 = tr_read<v_rd_off(D0, 1, 0)>(vb), h1 = tr_read<v_rd_off(D0, 1, 1)>(vb);
;     asm volatile("s_waitcnt lgkmcnt(0)" ::: "memory"); SBAR();
;     const bf16x8 v0 = PKV(l0, h0), v1 = PKV(l1, h1);
;     oa = MFMA(a0, v0, oa); ob = MFMA(b0, v0, ob); oa = MFMA(a1, v1, oa); ob = MFMA(b1, v1, ob); }
;   { const s16x4 l2 = tr_read<v_rd_off(D0, 2, 0)>(vb), h2 = tr_read<v_rd_off(D0, 2, 1)>(vb), l3 = tr_read<v_rd_off(D0, 3, 0)>(vb), h3 = tr_read<v_rd_off(D0, 3, 1)>(vb);
;     asm volatile("s_waitcnt lgkmcnt(0)" ::: "memory"); SBAR();
;     const bf16x8 v2 = PKV(l2, h2), v3 = PKV(l3, h3);
;     oa = MFMA(a2, v2, oa); ob = MFMA(b2, v2, ob); oa = MFMA(a3, v3, oa); ob = MFMA(b3, v3, ob); }
;     ...
; }
; __device__ __forceinline__ void att_qkt(f32x16& p0, f32x16& p1, const char* Kb, const bf16x8 (&qr)[4], int koff, int ksw, int hi) {
;   p0 = f32x16{}; p1 = f32x16{};
; #pragma unroll
;   for (int d0 = 0; d0 < 4; ++d0) {
;     const int co = ((d0 * 2 + hi) ^ ksw) << 4;
;     const bf16x8 b0 = *(const bf16x8*)(Kb + koff + co);
;     const bf16x8 b1 = *(const bf16x8*)(Kb + koff + 4096 + co);
;     p0 = MFMA(b0, qr[d0], p0); p1 = MFMA(b1, qr[d0], p1);
;   }
; }
; __device__ __forceinline__ void sm_fixed(f32x16& p0, f32x16& p1, float mC, float& l_reg, bf16x8& pa0, bf16x8& pa1, bf16x8& pa2, bf16x8& pa3) {
;   constexpr float C = 1.4426950408889634f;
; #pragma unroll
;   for (int r = 0; r < 16; ++r) p0[r] = __builtin_amdgcn_exp2f(fmaf(p0[r], C, -mC));
; #pragma unroll
;   for (int r = 0; r < 16; ++r) p1[r] = __builtin_amdgcn_exp2f(fmaf(p1[r], C, -mC));
;   float ps = 0;
; #pragma unroll
;   for (int r = 0; r < 16; ++r) ps += p0[r];
; #pragma unroll
;   for (int r = 0; r < 16; ++r) ps += p1[r];
;   { auto rr = __builtin_amdgcn_permlane32_swap(__float_as_uint(ps), __float_as_uint(ps), false, false);
;     ps = __uint_as_float(rr[0]) + __uint_as_float(rr[1]); }
;   l_reg += ps;
;     ...
;   PK4N(p0, 0, pa0); PK4N(p0, 8, pa1); PK4N(p1, 0, pa2); PK4N(p1, 8, pa3);
;     ...
; }
; #pragma unroll
	v_mfma_f32_32x32x16_bf16 v[144:159], v[240:243], v[180:183], 0
	ds_read_b64_tr_b16 v[240:241], v234 offset:12288
	ds_read_b64_tr_b16 v[242:243], v234 offset:14336
	v_exp_f32_e32 v134, v134
	v_exp_f32_e32 v135, v135
	v_add_f32_e32 v204, v204, v132
	v_add_f32_e32 v204, v204, v133
	v_cvt_pk_bf16_f32 v186, v132, v133
	s_waitcnt lgkmcnt(4)
	v_mfma_f32_32x32x16_bf16 v[144:159], v[244:247], v[176:179], v[144:159]
	ds_read_b64_tr_b16 v[244:245], v234 offset:12800
	ds_read_b64_tr_b16 v[246:247], v234 offset:14848
	v_fmamk_f32 v136, v136, 0x3fb8aa3b, v233
	v_fmamk_f32 v137, v137, 0x3fb8aa3b, v233
	v_exp_f32_e32 v136, v136
	v_exp_f32_e32 v137, v137
	v_add_f32_e32 v204, v204, v134
	s_waitcnt lgkmcnt(5)
	v_mfma_f32_32x32x16_bf16 v[144:159], v[218:221], v[172:175], v[144:159]
	ds_read_b64_tr_b16 v[218:219], v234 offset:13312
	ds_read_b64_tr_b16 v[220:221], v234 offset:15360
	v_add_f32_e32 v204, v204, v135
	v_cvt_pk_bf16_f32 v187, v134, v135
	v_fmamk_f32 v138, v138, 0x3fb8aa3b, v233
	v_fmamk_f32 v139, v139, 0x3fb8aa3b, v233
	v_exp_f32_e32 v138, v138
	s_waitcnt lgkmcnt(6)
	v_mfma_f32_32x32x16_bf16 v[144:159], v[210:213], v[168:171], v[144:159]
	ds_read_b64_tr_b16 v[210:211], v234 offset:13824
	ds_read_b64_tr_b16 v[212:213], v234 offset:15872
	v_exp_f32_e32 v139, v139
	v_add_f32_e32 v204, v204, v136
	v_add_f32_e32 v204, v204, v137
	v_cvt_pk_bf16_f32 v188, v136, v137
	v_fmamk_f32 v140, v140, 0x3fb8aa3b, v233
	s_waitcnt lgkmcnt(6)
	v_mfma_f32_32x32x16_bf16 v[0:15], v[196:199], v[240:243], v[0:15]
	ds_read_b128 v[240:243], v239 offset:40960
	v_fmamk_f32 v141, v141, 0x3fb8aa3b, v233
	v_exp_f32_e32 v140, v140
	v_exp_f32_e32 v141, v141
	v_add_f32_e32 v204, v204, v138
	s_waitcnt lgkmcnt(5)
	v_mfma_f32_32x32x16_bf16 v[16:31], v[196:199], v[244:247], v[16:31]
	ds_read_b128 v[244:247], v238 offset:40960
	v_add_f32_e32 v204, v204, v139
	v_cvt_pk_bf16_f32 v189, v138, v139
	v_fmamk_f32 v142, v142, 0x3fb8aa3b, v233
	v_fmamk_f32 v143, v143, 0x3fb8aa3b, v233
	s_waitcnt lgkmcnt(4)
	v_mfma_f32_32x32x16_bf16 v[32:47], v[196:199], v[218:221], v[32:47]
	ds_read_b128 v[218:221], v237 offset:40960
	v_exp_f32_e32 v142, v142
	v_exp_f32_e32 v143, v143
	v_add_f32_e32 v204, v204, v140
	v_add_f32_e32 v204, v204, v141
	s_waitcnt lgkmcnt(3)
	v_mfma_f32_32x32x16_bf16 v[48:63], v[196:199], v[210:213], v[48:63]
	ds_read_b128 v[210:213], v230 offset:0
	v_cvt_pk_bf16_f32 v190, v140, v141
	v_add_f32_e32 v204, v204, v142
	v_add_f32_e32 v204, v204, v143
	v_cvt_pk_bf16_f32 v191, v142, v143
	s_waitcnt vmcnt(4)
	s_barrier
	s_waitcnt lgkmcnt(3)
	v_mfma_f32_32x32x16_bf16 v[128:143], v[240:243], v[164:167], 0
	ds_read_b128 v[240:243], v235 offset:40960
	v_fmamk_f32 v144, v144, 0x3fb8aa3b, v233
	v_fmamk_f32 v145, v145, 0x3fb8aa3b, v233
	v_exp_f32_e32 v144, v144
	v_exp_f32_e32 v145, v145
	v_fmamk_f32 v146, v146, 0x3fb8aa3b, v233
	s_add_u32 m0, s7, 0x4000
	s_nop 0
	global_load_lds_dwordx4 v249, s[98:99]
	s_waitcnt lgkmcnt(3)
	v_mfma_f32_32x32x16_bf16 v[128:143], v[244:247], v[160:163], v[128:143]
	ds_read_b128 v[244:247], v230 offset:4096
	v_fmamk_f32 v147, v147, 0x3fb8aa3b, v233
	v_exp_f32_e32 v146, v146
	v_exp_f32_e32 v147, v147
	v_add_f32_e32 v204, v204, v144
	v_add_f32_e32 v204, v204, v145
	s_add_u32 m0, s7, 0x5000
	s_add_u32 s18, s98, 0x16000
	s_addc_u32 s19, s99, 0
	global_load_lds_dwordx4 v249, s[18:19]
	s_waitcnt lgkmcnt(2)
	v_mfma_f32_32x32x16_bf16 v[128:143], v[218:221], v[210:213], v[128:143]
	ds_read_b64_tr_b16 v[218:219], v234 offset:32768
	ds_read_b64_tr_b16 v[220:221], v234 offset:34816
	ds_read_b64_tr_b16 v[210:211], v234 offset:33280
	ds_read_b64_tr_b16 v[212:213], v234 offset:35328
	v_cvt_pk_bf16_f32 v192, v144, v145
	v_fmamk_f32 v148, v148, 0x3fb8aa3b, v233
	v_fmamk_f32 v149, v149, 0x3fb8aa3b, v233
	v_exp_f32_e32 v148, v148
	v_exp_f32_e32 v149, v149
	s_add_u32 m0, s7, 0x6000
	s_add_u32 s18, s98, 0x2c000
	s_addc_u32 s19, s99, 0
	global_load_lds_dwordx4 v249, s[18:19]
	s_waitcnt lgkmcnt(4)
	v_mfma_f32_32x32x16_bf16 v[128:143], v[240:243], v[244:247], v[128:143]
	ds_read_b64_tr_b16 v[240:241], v234 offset:33792
	ds_read_b64_tr_b16 v[242:243], v234 offset:35840
	ds_read_b64_tr_b16 v[244:245], v234 offset:34304
	ds_read_b64_tr_b16 v[246:247], v234 offset:36352
	v_add_f32_e32 v204, v204, v146
	v_add_f32_e32 v204, v204, v147
	v_cvt_pk_bf16_f32 v193, v146, v147
	v_fmamk_f32 v150, v150, 0x3fb8aa3b, v233
	v_fmamk_f32 v151, v151, 0x3fb8aa3b, v233
	s_add_u32 m0, s7, 0x7000
	s_add_u32 s18, s98, 0x42000
	s_addc_u32 s19, s99, 0
	global_load_lds_dwordx4 v249, s[18:19]
	s_add_u32 s98, s98, 0x58000
	s_addc_u32 s99, s99, 0
	s_waitcnt lgkmcnt(6)
	v_mfma_f32_32x32x16_bf16 v[64:79], v[184:187], v[218:221], v[64:79]
	ds_read_b64_tr_b16 v[218:219], v234 offset:36864
	ds_read_b64_tr_b16 v[220:221], v234 offset:38912
	v_exp_f32_e32 v150, v150
	v_exp_f32_e32 v151, v151
	v_add_f32_e32 v204, v204, v148
	v_add_f32_e32 v204, v204, v149
	v_cvt_pk_bf16_f32 v194, v148, v149
	s_waitcnt lgkmcnt(6)
	v_mfma_f32_32x32x16_bf16 v[80:95], v[184:187], v[210:213], v[80:95]
	ds_read_b64_tr_b16 v[210:211], v234 offset:37376
	ds_read_b64_tr_b16 v[212:213], v234 offset:39424
	v_fmamk_f32 v152, v152, 0x3fb8aa3b, v233
	v_fmamk_f32 v153, v153, 0x3fb8aa3b, v233
	v_exp_f32_e32 v152, v152
	v_exp_f32_e32 v153, v153
	v_add_f32_e32 v204, v204, v150
	s_waitcnt lgkmcnt(6)
	v_mfma_f32_32x32x16_bf16 v[96:111], v[184:187], v[240:243], v[96:111]
	ds_read_b64_tr_b16 v[240:241], v234 offset:37888
	ds_read_b64_tr_b16 v[242:243], v234 offset:39936
	v_add_f32_e32 v204, v204, v151
	v_cvt_pk_bf16_f32 v195, v150, v151
	v_fmamk_f32 v154, v154, 0x3fb8aa3b, v233
	v_fmamk_f32 v155, v155, 0x3fb8aa3b, v233
	v_exp_f32_e32 v154, v154
	s_waitcnt lgkmcnt(6)
; #define SBAR() __builtin_amdgcn_sched_barrier(0)
; template <int D0> __device__ __forceinline__ void pv_two(f32x16& oa, f32x16& ob, int vb, bf16x8 a0, bf16x8 a1, bf16x8 a2, bf16x8 a3,
;                                                          bf16x8 b0, bf16x8 b1, bf16x8 b2, bf16x8 b3) {
;     ...
;   { const s16x4 l0 = tr_read<v_rd_off(D0, 0, 0)>(vb), h0 = tr_read<v_rd_off(D0, 0, 1)>(vb), l1 = tr_read<v_rd_off(D0, 1, 0)>(vb), h1 = tr_read<v_rd_off(D0, 1, 1)>(vb);
;     asm volatile("s_waitcnt lgkmcnt(0)" ::: "memory"); SBAR();
;     const bf16x8 v0 = PKV(l0, h0), v1 = PKV(l1, h1);
;     oa = MFMA(a0, v0, oa); ob = MFMA(b0, v0, ob); oa = MFMA(a1, v1, oa); ob = MFMA(b1, v1, ob); }
;   { const s16x4 l2 = tr_read<v_rd_off(D0, 2, 0)>(vb), h2 = tr_read<v_rd_off(D0, 2, 1)>(vb), l3 = tr_read<v_rd_off(D0, 3, 0)>(vb), h3 = tr_read<v_rd_off(D0, 3, 1)>(vb);
;     asm volatile("s_waitcnt lgkmcnt(0)" ::: "memory"); SBAR();
;     const bf16x8 v2 = PKV(l2, h2), v3 = PKV(l3, h3);
;     oa = MFMA(a2, v2, oa); ob = MFMA(b2, v2, ob); oa = MFMA(a3, v3, oa); ob = MFMA(b3, v3, ob); }
;     ...
; }
; __device__ __forceinline__ void att_qkt(f32x16& p0, f32x16& p1, const char* Kb, const bf16x8 (&qr)[4], int koff, int ksw, int hi) {
;   p0 = f32x16{}; p1 = f32x16{};
; #pragma unroll
;   for (int d0 = 0; d0 < 4; ++d0) {
;     const int co = ((d0 * 2 + hi) ^ ksw) << 4;
;     const bf16x8 b0 = *(const bf16x8*)(Kb + koff + co);
;     const bf16x8 b1 = *(const bf16x8*)(Kb + koff + 4096 + co);
;     p0 = MFMA(b0, qr[d0], p0); p1 = MFMA(b1, qr[d0], p1);
;   }
; }
; __device__ __forceinline__ void sm_fixed(f32x16& p0, f32x16& p1, float mC, float& l_reg, bf16x8& pa0, bf16x8& pa1, bf16x8& pa2, bf16x8& pa3) {
;   constexpr float C = 1.4426950408889634f;
; #pragma unroll
;   for (int r = 0; r < 16; ++r) p0[r] = __builtin_amdgcn_exp2f(fmaf(p0[r], C, -mC));
; #pragma unroll
;   for (int r = 0; r < 16; ++r) p1[r] = __builtin_amdgcn_exp2f(fmaf(p1[r], C, -mC));
;   float ps = 0;
; #pragma unroll
;   for (int r = 0; r < 16; ++r) ps += p0[r];
; #pragma unroll
;   for (int r = 0; r < 16; ++r) ps += p1[r];
;   { auto rr = __builtin_amdgcn_permlane32_swap(__float_as_uint(ps), __float_as_uint(ps), false, false);
;     ps = __uint_as_float(rr[0]) + __uint_as_float(rr[1]); }
;   l_reg += ps;
;     ...
;   PK4N(p0, 0, pa0); PK4N(p0, 8, pa1); PK4N(p1, 0, pa2); PK4N(p1, 8, pa3);
;     ...
; }
; #pragma unroll
	v_mfma_f32_32x32x16_bf16 v[112:127], v[184:187], v[244:247], v[112:127]
	ds_read_b64_tr_b16 v[244:245], v234 offset:38400
	ds_read_b64_tr_b16 v[246:247], v234 offset:40448
	v_exp_f32_e32 v155, v155
	v_add_f32_e32 v204, v204, v152
	v_add_f32_e32 v204, v204, v153
	v_cvt_pk_bf16_f32 v196, v152, v153
	v_fmamk_f32 v156, v156, 0x3fb8aa3b, v233
	s_waitcnt lgkmcnt(6)
	v_mfma_f32_32x32x16_bf16 v[64:79], v[188:191], v[218:221], v[64:79]
	ds_read_b64_tr_b16 v[218:219], v234 offset:40960
	ds_read_b64_tr_b16 v[220:221], v234 offset:43008
	v_fmamk_f32 v157, v157, 0x3fb8aa3b, v233
	v_exp_f32_e32 v156, v156
	v_exp_f32_e32 v157, v157
	v_add_f32_e32 v204, v204, v154
	s_waitcnt lgkmcnt(6)
	v_mfma_f32_32x32x16_bf16 v[80:95], v[188:191], v[210:213], v[80:95]
	ds_read_b64_tr_b16 v[210:211], v234 offset:41472
	ds_read_b64_tr_b16 v[212:213], v234 offset:43520
	v_add_f32_e32 v204, v204, v155
	v_cvt_pk_bf16_f32 v197, v154, v155
	v_fmamk_f32 v158, v158, 0x3fb8aa3b, v233
	v_fmamk_f32 v159, v159, 0x3fb8aa3b, v233
	s_waitcnt lgkmcnt(6)
	v_mfma_f32_32x32x16_bf16 v[96:111], v[188:191], v[240:243], v[96:111]
	ds_read_b64_tr_b16 v[240:241], v234 offset:41984
	ds_read_b64_tr_b16 v[242:243], v234 offset:44032
	v_exp_f32_e32 v158, v158
	v_exp_f32_e32 v159, v159
	v_add_f32_e32 v204, v204, v156
	v_add_f32_e32 v204, v204, v157
	s_waitcnt lgkmcnt(6)
	v_mfma_f32_32x32x16_bf16 v[112:127], v[188:191], v[244:247], v[112:127]
	ds_read_b64_tr_b16 v[244:245], v234 offset:42496
	ds_read_b64_tr_b16 v[246:247], v234 offset:44544
	v_cvt_pk_bf16_f32 v198, v156, v157
	v_add_f32_e32 v204, v204, v158
	v_add_f32_e32 v204, v204, v159
	v_cvt_pk_bf16_f32 v199, v158, v159
	s_waitcnt lgkmcnt(6)
	v_mfma_f32_32x32x16_bf16 v[64:79], v[192:195], v[218:221], v[64:79]
	ds_read_b128 v[218:221], v239 offset:45056
	v_fmamk_f32 v128, v128, 0x3fb8aa3b, v231
	v_fmamk_f32 v129, v129, 0x3fb8aa3b, v231
	v_exp_f32_e32 v128, v128
	v_exp_f32_e32 v129, v129
	v_fmamk_f32 v130, v130, 0x3fb8aa3b, v231
	s_waitcnt lgkmcnt(5)
	v_mfma_f32_32x32x16_bf16 v[80:95], v[192:195], v[210:213], v[80:95]
	ds_read_b128 v[210:213], v238 offset:45056
	v_fmamk_f32 v131, v131, 0x3fb8aa3b, v231
	v_exp_f32_e32 v130, v130
	v_exp_f32_e32 v131, v131
	v_add_f32_e32 v205, v205, v128
	v_add_f32_e32 v205, v205, v129
	s_waitcnt lgkmcnt(4)
	v_mfma_f32_32x32x16_bf16 v[96:111], v[192:195], v[240:243], v[96:111]
	ds_read_b128 v[240:243], v237 offset:45056
	v_cvt_pk_bf16_f32 v184, v128, v129
	v_fmamk_f32 v132, v132, 0x3fb8aa3b, v231
	v_fmamk_f32 v133, v133, 0x3fb8aa3b, v231
	v_exp_f32_e32 v132, v132
	v_exp_f32_e32 v133, v133
	s_waitcnt lgkmcnt(3)
	v_mfma_f32_32x32x16_bf16 v[112:127], v[192:195], v[244:247], v[112:127]
	ds_read_b128 v[244:247], v230 offset:0
	v_add_f32_e32 v205, v205, v130
	v_add_f32_e32 v205, v205, v131
	v_cvt_pk_bf16_f32 v185, v130, v131
	v_fmamk_f32 v134, v134, 0x3fb8aa3b, v231
	v_fmamk_f32 v135, v135, 0x3fb8aa3b, v231
	s_waitcnt lgkmcnt(3)
	v_mfma_f32_32x32x16_bf16 v[144:159], v[218:221], v[164:167], 0
	ds_read_b128 v[218:221], v235 offset:45056
	v_exp_f32_e32 v134, v134
	v_exp_f32_e32 v135, v135
	v_add_f32_e32 v205, v205, v132
	v_add_f32_e32 v205, v205, v133
	v_cvt_pk_bf16_f32 v186, v132, v133
	s_waitcnt lgkmcnt(3)
	v_mfma_f32_32x32x16_bf16 v[144:159], v[210:213], v[160:163], v[144:159]
	ds_read_b128 v[210:213], v230 offset:4096
	v_fmamk_f32 v136, v136, 0x3fb8aa3b, v231
	v_fmamk_f32 v137, v137, 0x3fb8aa3b, v231
	v_exp_f32_e32 v136, v136
	v_exp_f32_e32 v137, v137
	v_add_f32_e32 v205, v205, v134
	s_waitcnt lgkmcnt(2)
	v_mfma_f32_32x32x16_bf16 v[144:159], v[240:243], v[244:247], v[144:159]
	ds_read_b64_tr_b16 v[240:241], v234 offset:45056
	ds_read_b64_tr_b16 v[242:243], v234 offset:47104
	ds_read_b64_tr_b16 v[244:245], v234 offset:45568
	ds_read_b64_tr_b16 v[246:247], v234 offset:47616
	v_add_f32_e32 v205, v205, v135
	v_cvt_pk_bf16_f32 v187, v134, v135
	v_fmamk_f32 v138, v138, 0x3fb8aa3b, v231
	v_fmamk_f32 v139, v139, 0x3fb8aa3b, v231
	v_exp_f32_e32 v138, v138
	s_waitcnt lgkmcnt(4)
	v_mfma_f32_32x32x16_bf16 v[144:159], v[218:221], v[210:213], v[144:159]
	ds_read_b64_tr_b16 v[218:219], v234 offset:46080
	ds_read_b64_tr_b16 v[220:221], v234 offset:48128
	ds_read_b64_tr_b16 v[210:211], v234 offset:46592
	ds_read_b64_tr_b16 v[212:213], v234 offset:48640
	v_exp_f32_e32 v139, v139
	v_add_f32_e32 v205, v205, v136
	v_add_f32_e32 v205, v205, v137
	v_cvt_pk_bf16_f32 v188, v136, v137
	v_fmamk_f32 v140, v140, 0x3fb8aa3b, v231
	s_waitcnt lgkmcnt(6)
	v_mfma_f32_32x32x16_bf16 v[64:79], v[196:199], v[240:243], v[64:79]
	ds_read_b64_tr_b16 v[240:241], v234 offset:32768
	ds_read_b64_tr_b16 v[242:243], v234 offset:34816
	v_fmamk_f32 v141, v141, 0x3fb8aa3b, v231
	v_exp_f32_e32 v140, v140
	v_exp_f32_e32 v141, v141
	v_add_f32_e32 v205, v205, v138
	s_waitcnt lgkmcnt(6)
	v_mfma_f32_32x32x16_bf16 v[80:95], v[196:199], v[244:247], v[80:95]
	ds_read_b64_tr_b16 v[244:245], v234 offset:33280
	ds_read_b64_tr_b16 v[246:247], v234 offset:35328
	v_add_f32_e32 v205, v205, v139
	v_cvt_pk_bf16_f32 v189, v138, v139
	v_fmamk_f32 v142, v142, 0x3fb8aa3b, v231
	v_fmamk_f32 v143, v143, 0x3fb8aa3b, v231
	s_waitcnt lgkmcnt(6)
	v_mfma_f32_32x32x16_bf16 v[96:111], v[196:199], v[218:221], v[96:111]
	ds_read_b64_tr_b16 v[218:219], v234 offset:33792
	ds_read_b64_tr_b16 v[220:221], v234 offset:35840
	v_exp_f32_e32 v142, v142
	v_exp_f32_e32 v143, v143
	v_add_f32_e32 v205, v205, v140
	v_add_f32_e32 v205, v205, v141
	s_waitcnt lgkmcnt(6)
	v_mfma_f32_32x32x16_bf16 v[112:127], v[196:199], v[210:213], v[112:127]
	ds_read_b64_tr_b16 v[210:211], v234 offset:34304
	ds_read_b64_tr_b16 v[212:213], v234 offset:36352
	v_cvt_pk_bf16_f32 v190, v140, v141
	v_add_f32_e32 v205, v205, v142
	v_add_f32_e32 v205, v205, v143
	v_cvt_pk_bf16_f32 v191, v142, v143
	s_waitcnt vmcnt(4)
	s_barrier
; #define SBAR() __builtin_amdgcn_sched_barrier(0)
; template <int D0> __device__ __forceinline__ void pv_two(f32x16& oa, f32x16& ob, int vb, bf16x8 a0, bf16x8 a1, bf16x8 a2, bf16x8 a3,
;                                                          bf16x8 b0, bf16x8 b1, bf16x8 b2, bf16x8 b3) {
;     ...
;   { const s16x4 l0 = tr_read<v_rd_off(D0, 0, 0)>(vb), h0 = tr_read<v_rd_off(D0, 0, 1)>(vb), l1 = tr_read<v_rd_off(D0, 1, 0)>(vb), h1 = tr_read<v_rd_off(D0, 1, 1)>(vb);
;     asm volatile("s_waitcnt lgkmcnt(0)" ::: "memory"); SBAR();
;     const bf16x8 v0 = PKV(l0, h0), v1 = PKV(l1, h1);
;     oa = MFMA(a0, v0, oa); ob = MFMA(b0, v0, ob); oa = MFMA(a1, v1, oa); ob = MFMA(b1, v1, ob); }
;   { const s16x4 l2 = tr_read<v_rd_off(D0, 2, 0)>(vb), h2 = tr_read<v_rd_off(D0, 2, 1)>(vb), l3 = tr_read<v_rd_off(D0, 3, 0)>(vb), h3 = tr_read<v_rd_off(D0, 3, 1)>(vb);
;     asm volatile("s_waitcnt lgkmcnt(0)" ::: "memory"); SBAR();
;     const bf16x8 v2 = PKV(l2, h2), v3 = PKV(l3, h3);
;     oa = MFMA(a2, v2, oa); ob = MFMA(b2, v2, ob); oa = MFMA(a3, v3, oa); ob = MFMA(b3, v3, ob); }
;     ...
; }
; __device__ __forceinline__ void att_qkt(f32x16& p0, f32x16& p1, const char* Kb, const bf16x8 (&qr)[4], int koff, int ksw, int hi) {
;   p0 = f32x16{}; p1 = f32x16{};
; #pragma unroll
;   for (int d0 = 0; d0 < 4; ++d0) {
;     const int co = ((d0 * 2 + hi) ^ ksw) << 4;
;     const bf16x8 b0 = *(const bf16x8*)(Kb + koff + co);
;     const bf16x8 b1 = *(const bf16x8*)(Kb + koff + 4096 + co);
;     p0 = MFMA(b0, qr[d0], p0); p1 = MFMA(b1, qr[d0], p1);
;   }
; }
; __device__ __forceinline__ void sm_fixed(f32x16& p0, f32x16& p1, float mC, float& l_reg, bf16x8& pa0, bf16x8& pa1, bf16x8& pa2, bf16x8& pa3) {
;   constexpr float C = 1.4426950408889634f;
; #pragma unroll
;   for (int r = 0; r < 16; ++r) p0[r] = __builtin_amdgcn_exp2f(fmaf(p0[r], C, -mC));
; #pragma unroll
;   for (int r = 0; r < 16; ++r) p1[r] = __builtin_amdgcn_exp2f(fmaf(p1[r], C, -mC));
;   float ps = 0;
; #pragma unroll
;   for (int r = 0; r < 16; ++r) ps += p0[r];
; #pragma unroll
;   for (int r = 0; r < 16; ++r) ps += p1[r];
;   { auto rr = __builtin_amdgcn_permlane32_swap(__float_as_uint(ps), __float_as_uint(ps), false, false);
;     ps = __uint_as_float(rr[0]) + __uint_as_float(rr[1]); }
;   l_reg += ps;
;     ...
;   PK4N(p0, 0, pa0); PK4N(p0, 8, pa1); PK4N(p1, 0, pa2); PK4N(p1, 8, pa3);
;     ...
; }
; #pragma unroll
	s_waitcnt lgkmcnt(6)
	v_mfma_f32_32x32x16_bf16 v[0:15], v[184:187], v[240:243], v[0:15]
	ds_read_b128 v[240:243], v239 offset:0
	v_fmamk_f32 v144, v144, 0x3fb8aa3b, v231
	v_fmamk_f32 v145, v145, 0x3fb8aa3b, v231
	v_exp_f32_e32 v144, v144
	v_exp_f32_e32 v145, v145
	v_fmamk_f32 v146, v146, 0x3fb8aa3b, v231
	s_add_u32 m0, s7, 0x8000
	s_nop 0
	global_load_lds_dwordx4 v248, s[40:41]
	s_waitcnt lgkmcnt(5)
	v_mfma_f32_32x32x16_bf16 v[16:31], v[184:187], v[244:247], v[16:31]
	ds_read_b128 v[244:247], v238 offset:0
	v_fmamk_f32 v147, v147, 0x3fb8aa3b, v231
	v_exp_f32_e32 v146, v146
	v_exp_f32_e32 v147, v147
	v_add_f32_e32 v205, v205, v144
	v_add_f32_e32 v205, v205, v145
	s_add_u32 m0, s7, 0xa000
	s_add_u32 s18, s40, 0x80
	s_addc_u32 s19, s41, 0
	global_load_lds_dwordx4 v248, s[18:19]
	s_waitcnt lgkmcnt(4)
	v_mfma_f32_32x32x16_bf16 v[32:47], v[184:187], v[218:221], v[32:47]
	ds_read_b128 v[218:221], v237 offset:0
	v_cvt_pk_bf16_f32 v192, v144, v145
	v_fmamk_f32 v148, v148, 0x3fb8aa3b, v231
	v_fmamk_f32 v149, v149, 0x3fb8aa3b, v231
	v_exp_f32_e32 v148, v148
	v_exp_f32_e32 v149, v149
	s_add_u32 m0, s7, 0x9000
	s_add_u32 s18, s40, 0x2c000
	s_addc_u32 s19, s41, 0
	global_load_lds_dwordx4 v248, s[18:19]
	s_waitcnt lgkmcnt(3)
	v_mfma_f32_32x32x16_bf16 v[48:63], v[184:187], v[210:213], v[48:63]
	ds_read_b128 v[210:213], v235 offset:0
	v_add_f32_e32 v205, v205, v146
	v_add_f32_e32 v205, v205, v147
	v_cvt_pk_bf16_f32 v193, v146, v147
	v_fmamk_f32 v150, v150, 0x3fb8aa3b, v231
	v_fmamk_f32 v151, v151, 0x3fb8aa3b, v231
	s_add_u32 m0, s7, 0xb000
	s_add_u32 s18, s40, 0x2c080
	s_addc_u32 s19, s41, 0
	global_load_lds_dwordx4 v248, s[18:19]
	s_add_u32 s40, s40, 0x58000
	s_addc_u32 s41, s41, 0
	s_waitcnt lgkmcnt(3)
	v_mfma_f32_32x32x16_bf16 v[128:143], v[240:243], v[180:183], 0
	ds_read_b64_tr_b16 v[240:241], v234 offset:36864
	ds_read_b64_tr_b16 v[242:243], v234 offset:38912
	v_exp_f32_e32 v150, v150
	v_exp_f32_e32 v151, v151
	v_add_f32_e32 v205, v205, v148
	v_add_f32_e32 v205, v205, v149
	v_cvt_pk_bf16_f32 v194, v148, v149
	s_waitcnt lgkmcnt(4)
	v_mfma_f32_32x32x16_bf16 v[128:143], v[244:247], v[176:179], v[128:143]
	ds_read_b64_tr_b16 v[244:245], v234 offset:37376
	ds_read_b64_tr_b16 v[246:247], v234 offset:39424
	v_fmamk_f32 v152, v152, 0x3fb8aa3b, v231
	v_fmamk_f32 v153, v153, 0x3fb8aa3b, v231
	v_exp_f32_e32 v152, v152
	v_exp_f32_e32 v153, v153
	v_add_f32_e32 v205, v205, v150
	s_waitcnt lgkmcnt(5)
	v_mfma_f32_32x32x16_bf16 v[128:143], v[218:221], v[172:175], v[128:143]
	ds_read_b64_tr_b16 v[218:219], v234 offset:37888
	ds_read_b64_tr_b16 v[220:221], v234 offset:39936
	v_add_f32_e32 v205, v205, v151
	v_cvt_pk_bf16_f32 v195, v150, v151
	v_fmamk_f32 v154, v154, 0x3fb8aa3b, v231
	v_fmamk_f32 v155, v155, 0x3fb8aa3b, v231
	v_exp_f32_e32 v154, v154
	s_waitcnt lgkmcnt(6)
	v_mfma_f32_32x32x16_bf16 v[128:143], v[210:213], v[168:171], v[128:143]
	ds_read_b64_tr_b16 v[210:211], v234 offset:38400
	ds_read_b64_tr_b16 v[212:213], v234 offset:40448
	v_exp_f32_e32 v155, v155
	v_add_f32_e32 v205, v205, v152
	v_add_f32_e32 v205, v205, v153
	v_cvt_pk_bf16_f32 v196, v152, v153
	v_fmamk_f32 v156, v156, 0x3fb8aa3b, v231
	s_waitcnt lgkmcnt(6)
	v_mfma_f32_32x32x16_bf16 v[0:15], v[188:191], v[240:243], v[0:15]
	ds_read_b64_tr_b16 v[240:241], v234 offset:40960
	ds_read_b64_tr_b16 v[242:243], v234 offset:43008
	v_fmamk_f32 v157, v157, 0x3fb8aa3b, v231
	v_exp_f32_e32 v156, v156
	v_exp_f32_e32 v157, v157
	v_add_f32_e32 v205, v205, v154
	s_waitcnt lgkmcnt(6)
	v_mfma_f32_32x32x16_bf16 v[16:31], v[188:191], v[244:247], v[16:31]
	ds_read_b64_tr_b16 v[244:245], v234 offset:41472
	ds_read_b64_tr_b16 v[246:247], v234 offset:43520
	v_add_f32_e32 v205, v205, v155
	v_cvt_pk_bf16_f32 v197, v154, v155
	v_fmamk_f32 v158, v158, 0x3fb8aa3b, v231
	v_fmamk_f32 v159, v159, 0x3fb8aa3b, v231
	s_waitcnt lgkmcnt(6)
	v_mfma_f32_32x32x16_bf16 v[32:47], v[188:191], v[218:221], v[32:47]
	ds_read_b64_tr_b16 v[218:219], v234 offset:41984
	ds_read_b64_tr_b16 v[220:221], v234 offset:44032
	v_exp_f32_e32 v158, v158
	v_exp_f32_e32 v159, v159
	v_add_f32_e32 v205, v205, v156
	v_add_f32_e32 v205, v205, v157
	s_waitcnt lgkmcnt(6)
	v_mfma_f32_32x32x16_bf16 v[48:63], v[188:191], v[210:213], v[48:63]
	ds_read_b64_tr_b16 v[210:211], v234 offset:42496
	ds_read_b64_tr_b16 v[212:213], v234 offset:44544
	v_cvt_pk_bf16_f32 v198, v156, v157
	v_add_f32_e32 v205, v205, v158
	v_add_f32_e32 v205, v205, v159
	v_cvt_pk_bf16_f32 v199, v158, v159
	s_waitcnt lgkmcnt(6)
	v_mfma_f32_32x32x16_bf16 v[0:15], v[192:195], v[240:243], v[0:15]
	ds_read_b128 v[240:243], v239 offset:4096
	v_fmamk_f32 v128, v128, 0x3fb8aa3b, v233
	v_fmamk_f32 v129, v129, 0x3fb8aa3b, v233
	v_exp_f32_e32 v128, v128
	v_exp_f32_e32 v129, v129
	v_fmamk_f32 v130, v130, 0x3fb8aa3b, v233
	s_waitcnt lgkmcnt(5)
	v_mfma_f32_32x32x16_bf16 v[16:31], v[192:195], v[244:247], v[16:31]
	ds_read_b128 v[244:247], v238 offset:4096
	v_fmamk_f32 v131, v131, 0x3fb8aa3b, v233
	v_exp_f32_e32 v130, v130
	v_exp_f32_e32 v131, v131
	v_add_f32_e32 v204, v204, v128
	v_add_f32_e32 v204, v204, v129
	s_waitcnt lgkmcnt(4)
	v_mfma_f32_32x32x16_bf16 v[32:47], v[192:195], v[218:221], v[32:47]
	ds_read_b128 v[218:221], v237 offset:4096
	v_cvt_pk_bf16_f32 v184, v128, v129
	v_fmamk_f32 v132, v132, 0x3fb8aa3b, v233
	v_fmamk_f32 v133, v133, 0x3fb8aa3b, v233
	v_exp_f32_e32 v132, v132
	v_exp_f32_e32 v133, v133
	s_waitcnt lgkmcnt(3)
	v_mfma_f32_32x32x16_bf16 v[48:63], v[192:195], v[210:213], v[48:63]
	ds_read_b128 v[210:213], v235 offset:4096
	v_add_f32_e32 v204, v204, v130
	v_add_f32_e32 v204, v204, v131
	v_cvt_pk_bf16_f32 v185, v130, v131
	v_fmamk_f32 v134, v134, 0x3fb8aa3b, v233
	v_fmamk_f32 v135, v135, 0x3fb8aa3b, v233
	s_waitcnt lgkmcnt(3)
; #define SBAR() __builtin_amdgcn_sched_barrier(0)
; template <int D0> __device__ __forceinline__ void pv_two(f32x16& oa, f32x16& ob, int vb, bf16x8 a0, bf16x8 a1, bf16x8 a2, bf16x8 a3,
;                                                          bf16x8 b0, bf16x8 b1, bf16x8 b2, bf16x8 b3) {
;     ...
;   { const s16x4 l0 = tr_read<v_rd_off(D0, 0, 0)>(vb), h0 = tr_read<v_rd_off(D0, 0, 1)>(vb), l1 = tr_read<v_rd_off(D0, 1, 0)>(vb), h1 = tr_read<v_rd_off(D0, 1, 1)>(vb);
;     asm volatile("s_waitcnt lgkmcnt(0)" ::: "memory"); SBAR();
;     const bf16x8 v0 = PKV(l0, h0), v1 = PKV(l1, h1);
;     oa = MFMA(a0, v0, oa); ob = MFMA(b0, v0, ob); oa = MFMA(a1, v1, oa); ob = MFMA(b1, v1, ob); }
;   { const s16x4 l2 = tr_read<v_rd_off(D0, 2, 0)>(vb), h2 = tr_read<v_rd_off(D0, 2, 1)>(vb), l3 = tr_read<v_rd_off(D0, 3, 0)>(vb), h3 = tr_read<v_rd_off(D0, 3, 1)>(vb);
;     asm volatile("s_waitcnt lgkmcnt(0)" ::: "memory"); SBAR();
;     const bf16x8 v2 = PKV(l2, h2), v3 = PKV(l3, h3);
;     oa = MFMA(a2, v2, oa); ob = MFMA(b2, v2, ob); oa = MFMA(a3, v3, oa); ob = MFMA(b3, v3, ob); }
;     ...
; }
; __device__ __forceinline__ void att_qkt(f32x16& p0, f32x16& p1, const char* Kb, const bf16x8 (&qr)[4], int koff, int ksw, int hi) {
;   p0 = f32x16{}; p1 = f32x16{};
; #pragma unroll
;   for (int d0 = 0; d0 < 4; ++d0) {
;     const int co = ((d0 * 2 + hi) ^ ksw) << 4;
;     const bf16x8 b0 = *(const bf16x8*)(Kb + koff + co);
;     const bf16x8 b1 = *(const bf16x8*)(Kb + koff + 4096 + co);
;     p0 = MFMA(b0, qr[d0], p0); p1 = MFMA(b1, qr[d0], p1);
;   }
; }
; __device__ __forceinline__ void sm_fixed(f32x16& p0, f32x16& p1, float mC, float& l_reg, bf16x8& pa0, bf16x8& pa1, bf16x8& pa2, bf16x8& pa3) {
;   constexpr float C = 1.4426950408889634f;
; #pragma unroll
;   for (int r = 0; r < 16; ++r) p0[r] = __builtin_amdgcn_exp2f(fmaf(p0[r], C, -mC));
; #pragma unroll
;   for (int r = 0; r < 16; ++r) p1[r] = __builtin_amdgcn_exp2f(fmaf(p1[r], C, -mC));
;   float ps = 0;
; #pragma unroll
;   for (int r = 0; r < 16; ++r) ps += p0[r];
; #pragma unroll
;   for (int r = 0; r < 16; ++r) ps += p1[r];
;   { auto rr = __builtin_amdgcn_permlane32_swap(__float_as_uint(ps), __float_as_uint(ps), false, false);
;     ps = __uint_as_float(rr[0]) + __uint_as_float(rr[1]); }
;   l_reg += ps;
;     ...
;   PK4N(p0, 0, pa0); PK4N(p0, 8, pa1); PK4N(p1, 0, pa2); PK4N(p1, 8, pa3);
;     ...
; }
; #pragma unroll
	v_mfma_f32_32x32x16_bf16 v[144:159], v[240:243], v[180:183], 0
	ds_read_b64_tr_b16 v[240:241], v234 offset:45056
	ds_read_b64_tr_b16 v[242:243], v234 offset:47104
	v_exp_f32_e32 v134, v134
	v_exp_f32_e32 v135, v135
	v_add_f32_e32 v204, v204, v132
	v_add_f32_e32 v204, v204, v133
	v_cvt_pk_bf16_f32 v186, v132, v133
	s_waitcnt lgkmcnt(4)
	v_mfma_f32_32x32x16_bf16 v[144:159], v[244:247], v[176:179], v[144:159]
	ds_read_b64_tr_b16 v[244:245], v234 offset:45568
	ds_read_b64_tr_b16 v[246:247], v234 offset:47616
	v_fmamk_f32 v136, v136, 0x3fb8aa3b, v233
	v_fmamk_f32 v137, v137, 0x3fb8aa3b, v233
	v_exp_f32_e32 v136, v136
	v_exp_f32_e32 v137, v137
	v_add_f32_e32 v204, v204, v134
	s_waitcnt lgkmcnt(5)
	v_mfma_f32_32x32x16_bf16 v[144:159], v[218:221], v[172:175], v[144:159]
	ds_read_b64_tr_b16 v[218:219], v234 offset:46080
	ds_read_b64_tr_b16 v[220:221], v234 offset:48128
	v_add_f32_e32 v204, v204, v135
	v_cvt_pk_bf16_f32 v187, v134, v135
	v_fmamk_f32 v138, v138, 0x3fb8aa3b, v233
	v_fmamk_f32 v139, v139, 0x3fb8aa3b, v233
	v_exp_f32_e32 v138, v138
	s_waitcnt lgkmcnt(6)
	v_mfma_f32_32x32x16_bf16 v[144:159], v[210:213], v[168:171], v[144:159]
	ds_read_b64_tr_b16 v[210:211], v234 offset:46592
	ds_read_b64_tr_b16 v[212:213], v234 offset:48640
	v_exp_f32_e32 v139, v139
	v_add_f32_e32 v204, v204, v136
	v_add_f32_e32 v204, v204, v137
	v_cvt_pk_bf16_f32 v188, v136, v137
	v_fmamk_f32 v140, v140, 0x3fb8aa3b, v233
	s_waitcnt lgkmcnt(6)
	v_mfma_f32_32x32x16_bf16 v[0:15], v[196:199], v[240:243], v[0:15]
	ds_read_b128 v[240:243], v239 offset:8192
	v_fmamk_f32 v141, v141, 0x3fb8aa3b, v233
	v_exp_f32_e32 v140, v140
	v_exp_f32_e32 v141, v141
	v_add_f32_e32 v204, v204, v138
	s_waitcnt lgkmcnt(5)
	v_mfma_f32_32x32x16_bf16 v[16:31], v[196:199], v[244:247], v[16:31]
	ds_read_b128 v[244:247], v238 offset:8192
	v_add_f32_e32 v204, v204, v139
	v_cvt_pk_bf16_f32 v189, v138, v139
	v_fmamk_f32 v142, v142, 0x3fb8aa3b, v233
	v_fmamk_f32 v143, v143, 0x3fb8aa3b, v233
	s_waitcnt lgkmcnt(4)
	v_mfma_f32_32x32x16_bf16 v[32:47], v[196:199], v[218:221], v[32:47]
	ds_read_b128 v[218:221], v237 offset:8192
	v_exp_f32_e32 v142, v142
	v_exp_f32_e32 v143, v143
	v_add_f32_e32 v204, v204, v140
	v_add_f32_e32 v204, v204, v141
	s_waitcnt lgkmcnt(3)
	v_mfma_f32_32x32x16_bf16 v[48:63], v[196:199], v[210:213], v[48:63]
	ds_read_b128 v[210:213], v230 offset:0
	v_cvt_pk_bf16_f32 v190, v140, v141
	v_add_f32_e32 v204, v204, v142
	v_add_f32_e32 v204, v204, v143
	v_cvt_pk_bf16_f32 v191, v142, v143
	s_branch .Lattn_loop
.Lattn_exit:
	s_waitcnt lgkmcnt(6)
	v_mfma_f32_32x32x16_bf16 v[0:15], v[184:187], v[240:243], v[0:15]
	ds_read_b64_tr_b16 v[240:241], v234 offset:4096
	ds_read_b64_tr_b16 v[242:243], v234 offset:6144
	v_fmamk_f32 v144, v144, 0x3fb8aa3b, v231
	v_fmamk_f32 v145, v145, 0x3fb8aa3b, v231
	v_exp_f32_e32 v144, v144
	v_exp_f32_e32 v145, v145
	v_fmamk_f32 v146, v146, 0x3fb8aa3b, v231
	v_fmamk_f32 v147, v147, 0x3fb8aa3b, v231
	v_exp_f32_e32 v146, v146
	s_waitcnt lgkmcnt(6)
	v_mfma_f32_32x32x16_bf16 v[16:31], v[184:187], v[244:247], v[16:31]
	ds_read_b64_tr_b16 v[244:245], v234 offset:4608
	ds_read_b64_tr_b16 v[246:247], v234 offset:6656
	v_exp_f32_e32 v147, v147
	v_add_f32_e32 v205, v205, v144
	v_add_f32_e32 v205, v205, v145
	v_cvt_pk_bf16_f32 v192, v144, v145
	v_fmamk_f32 v148, v148, 0x3fb8aa3b, v231
	v_fmamk_f32 v149, v149, 0x3fb8aa3b, v231
	v_exp_f32_e32 v148, v148
	s_waitcnt lgkmcnt(6)
	v_mfma_f32_32x32x16_bf16 v[32:47], v[184:187], v[218:221], v[32:47]
	ds_read_b64_tr_b16 v[218:219], v234 offset:5120
	ds_read_b64_tr_b16 v[220:221], v234 offset:7168
	v_exp_f32_e32 v149, v149
	v_add_f32_e32 v205, v205, v146
	v_add_f32_e32 v205, v205, v147
	v_cvt_pk_bf16_f32 v193, v146, v147
	v_fmamk_f32 v150, v150, 0x3fb8aa3b, v231
	v_fmamk_f32 v151, v151, 0x3fb8aa3b, v231
	v_exp_f32_e32 v150, v150
	s_waitcnt lgkmcnt(6)
	v_mfma_f32_32x32x16_bf16 v[48:63], v[184:187], v[210:213], v[48:63]
	ds_read_b64_tr_b16 v[210:211], v234 offset:5632
	ds_read_b64_tr_b16 v[212:213], v234 offset:7680
	v_exp_f32_e32 v151, v151
	v_add_f32_e32 v205, v205, v148
	v_add_f32_e32 v205, v205, v149
	v_cvt_pk_bf16_f32 v194, v148, v149
	v_fmamk_f32 v152, v152, 0x3fb8aa3b, v231
	v_fmamk_f32 v153, v153, 0x3fb8aa3b, v231
	v_exp_f32_e32 v152, v152
	s_waitcnt lgkmcnt(6)
	v_mfma_f32_32x32x16_bf16 v[0:15], v[188:191], v[240:243], v[0:15]
	ds_read_b64_tr_b16 v[240:241], v234 offset:8192
	ds_read_b64_tr_b16 v[242:243], v234 offset:10240
	v_exp_f32_e32 v153, v153
	v_add_f32_e32 v205, v205, v150
	v_add_f32_e32 v205, v205, v151
	v_cvt_pk_bf16_f32 v195, v150, v151
	v_fmamk_f32 v154, v154, 0x3fb8aa3b, v231
	v_fmamk_f32 v155, v155, 0x3fb8aa3b, v231
	v_exp_f32_e32 v154, v154
	s_waitcnt lgkmcnt(6)
	v_mfma_f32_32x32x16_bf16 v[16:31], v[188:191], v[244:247], v[16:31]
	ds_read_b64_tr_b16 v[244:245], v234 offset:8704
	ds_read_b64_tr_b16 v[246:247], v234 offset:10752
	v_exp_f32_e32 v155, v155
	v_add_f32_e32 v205, v205, v152
	v_add_f32_e32 v205, v205, v153
	v_cvt_pk_bf16_f32 v196, v152, v153
	v_fmamk_f32 v156, v156, 0x3fb8aa3b, v231
	v_fmamk_f32 v157, v157, 0x3fb8aa3b, v231
	v_exp_f32_e32 v156, v156
	s_waitcnt lgkmcnt(6)
	v_mfma_f32_32x32x16_bf16 v[32:47], v[188:191], v[218:221], v[32:47]
	ds_read_b64_tr_b16 v[218:219], v234 offset:9216
	ds_read_b64_tr_b16 v[220:221], v234 offset:11264
	v_exp_f32_e32 v157, v157
	v_add_f32_e32 v205, v205, v154
	v_add_f32_e32 v205, v205, v155
	v_cvt_pk_bf16_f32 v197, v154, v155
	v_fmamk_f32 v158, v158, 0x3fb8aa3b, v231
	v_fmamk_f32 v159, v159, 0x3fb8aa3b, v231
	v_exp_f32_e32 v158, v158
	s_waitcnt lgkmcnt(6)
; #define SBAR() __builtin_amdgcn_sched_barrier(0)
; template <int D0> __device__ __forceinline__ void pv_two(f32x16& oa, f32x16& ob, int vb, bf16x8 a0, bf16x8 a1, bf16x8 a2, bf16x8 a3,
;                                                          bf16x8 b0, bf16x8 b1, bf16x8 b2, bf16x8 b3) {
;     ...
;   { const s16x4 l0 = tr_read<v_rd_off(D0, 0, 0)>(vb), h0 = tr_read<v_rd_off(D0, 0, 1)>(vb), l1 = tr_read<v_rd_off(D0, 1, 0)>(vb), h1 = tr_read<v_rd_off(D0, 1, 1)>(vb);
;     asm volatile("s_waitcnt lgkmcnt(0)" ::: "memory"); SBAR();
;     const bf16x8 v0 = PKV(l0, h0), v1 = PKV(l1, h1);
;     oa = MFMA(a0, v0, oa); ob = MFMA(b0, v0, ob); oa = MFMA(a1, v1, oa); ob = MFMA(b1, v1, ob); }
;   { const s16x4 l2 = tr_read<v_rd_off(D0, 2, 0)>(vb), h2 = tr_read<v_rd_off(D0, 2, 1)>(vb), l3 = tr_read<v_rd_off(D0, 3, 0)>(vb), h3 = tr_read<v_rd_off(D0, 3, 1)>(vb);
;     asm volatile("s_waitcnt lgkmcnt(0)" ::: "memory"); SBAR();
;     const bf16x8 v2 = PKV(l2, h2), v3 = PKV(l3, h3);
;     oa = MFMA(a2, v2, oa); ob = MFMA(b2, v2, ob); oa = MFMA(a3, v3, oa); ob = MFMA(b3, v3, ob); }
;     ...
; }
; __device__ __forceinline__ void att_qkt(f32x16& p0, f32x16& p1, const char* Kb, const bf16x8 (&qr)[4], int koff, int ksw, int hi) {
;   p0 = f32x16{}; p1 = f32x16{};
; #pragma unroll
;   for (int d0 = 0; d0 < 4; ++d0) {
;     const int co = ((d0 * 2 + hi) ^ ksw) << 4;
;     const bf16x8 b0 = *(const bf16x8*)(Kb + koff + co);
;     const bf16x8 b1 = *(const bf16x8*)(Kb + koff + 4096 + co);
;     p0 = MFMA(b0, qr[d0], p0); p1 = MFMA(b1, qr[d0], p1);
;   }
; }
; __device__ __forceinline__ void sm_fixed(f32x16& p0, f32x16& p1, float mC, float& l_reg, bf16x8& pa0, bf16x8& pa1, bf16x8& pa2, bf16x8& pa3) {
;   constexpr float C = 1.4426950408889634f;
; #pragma unroll
;   for (int r = 0; r < 16; ++r) p0[r] = __builtin_amdgcn_exp2f(fmaf(p0[r], C, -mC));
; #pragma unroll
;   for (int r = 0; r < 16; ++r) p1[r] = __builtin_amdgcn_exp2f(fmaf(p1[r], C, -mC));
;   float ps = 0;
; #pragma unroll
;   for (int r = 0; r < 16; ++r) ps += p0[r];
; #pragma unroll
;   for (int r = 0; r < 16; ++r) ps += p1[r];
;   { auto rr = __builtin_amdgcn_permlane32_swap(__float_as_uint(ps), __float_as_uint(ps), false, false);
;     ps = __uint_as_float(rr[0]) + __uint_as_float(rr[1]); }
;   l_reg += ps;
;     ...
;   PK4N(p0, 0, pa0); PK4N(p0, 8, pa1); PK4N(p1, 0, pa2); PK4N(p1, 8, pa3);
;     ...
; }
	v_mfma_f32_32x32x16_bf16 v[48:63], v[188:191], v[210:213], v[48:63]
	ds_read_b64_tr_b16 v[210:211], v234 offset:9728
	ds_read_b64_tr_b16 v[212:213], v234 offset:11776
	v_exp_f32_e32 v159, v159
	v_add_f32_e32 v205, v205, v156
	v_add_f32_e32 v205, v205, v157
	v_cvt_pk_bf16_f32 v198, v156, v157
	v_add_f32_e32 v205, v205, v158
	v_add_f32_e32 v205, v205, v159
	v_cvt_pk_bf16_f32 v199, v158, v159
	s_waitcnt lgkmcnt(6)
	v_mfma_f32_32x32x16_bf16 v[0:15], v[192:195], v[240:243], v[0:15]
	ds_read_b64_tr_b16 v[240:241], v234 offset:12288
	ds_read_b64_tr_b16 v[242:243], v234 offset:14336
	s_waitcnt lgkmcnt(6)
	v_mfma_f32_32x32x16_bf16 v[16:31], v[192:195], v[244:247], v[16:31]
	ds_read_b64_tr_b16 v[244:245], v234 offset:12800
	ds_read_b64_tr_b16 v[246:247], v234 offset:14848
	s_waitcnt lgkmcnt(6)
	v_mfma_f32_32x32x16_bf16 v[32:47], v[192:195], v[218:221], v[32:47]
	ds_read_b64_tr_b16 v[218:219], v234 offset:13312
	ds_read_b64_tr_b16 v[220:221], v234 offset:15360
	s_waitcnt lgkmcnt(6)
	v_mfma_f32_32x32x16_bf16 v[48:63], v[192:195], v[210:213], v[48:63]
	ds_read_b64_tr_b16 v[210:211], v234 offset:13824
	ds_read_b64_tr_b16 v[212:213], v234 offset:15872
	s_waitcnt lgkmcnt(6)
	v_mfma_f32_32x32x16_bf16 v[0:15], v[196:199], v[240:243], v[0:15]
	s_waitcnt lgkmcnt(4)
	v_mfma_f32_32x32x16_bf16 v[16:31], v[196:199], v[244:247], v[16:31]
	s_waitcnt lgkmcnt(2)
	v_mfma_f32_32x32x16_bf16 v[32:47], v[196:199], v[218:221], v[32:47]
	s_waitcnt lgkmcnt(0)
	v_mfma_f32_32x32x16_bf16 v[48:63], v[196:199], v[210:213], v[48:63]
	v_sub_u32_e32 v239, v239, v236
	v_sub_u32_e32 v238, v238, v236
	v_sub_u32_e32 v237, v237, v236
	v_sub_u32_e32 v235, v235, v236
	v_mov_b32_e32 v210, v204
	v_mov_b32_e32 v212, v204
	v_mov_b32_e32 v211, v205
	v_mov_b32_e32 v213, v205
	s_nop 1
	v_permlane32_swap_b32_e32 v210, v212
	v_permlane32_swap_b32_e32 v211, v213
	s_nop 1
	v_add_f32_e32 v204, v210, v212
	v_add_f32_e32 v205, v211, v213
	s_setprio 0
	s_setprio 0
	v_add_u32_e32 v198, v236, v239
	s_waitcnt vmcnt(0)
	s_waitcnt vmcnt(0)
	s_barrier
	ds_read_b128 v[128:131], v198 offset:32768
	ds_read_b128 v[132:135], v198 offset:36864
	v_add_u32_e32 v199, v236, v238
	s_waitcnt lgkmcnt(1)
	v_mfma_f32_32x32x16_bf16 v[144:159], v[128:131], v[180:183], 0
	v_add_u32_e32 v206, v236, v237
	ds_read_b128 v[186:189], v199 offset:36864
	v_add_u32_e32 v207, v236, v235
	v_and_b32_e32 v184, 0x3fffffc0, v214
	s_add_i32 s3, 0, 0x10000
	ds_read_b128 v[190:193], v206 offset:36864
	v_lshl_add_u32 v184, v184, 2, s3
	s_waitcnt lgkmcnt(2)
	v_mfma_f32_32x32x16_bf16 v[128:143], v[132:135], v[180:183], 0
	ds_read_b128 v[180:183], v199 offset:32768
	v_add_u32_e32 v185, 0x8000, v234
	ds_read_b128 v[194:197], v207 offset:36864
	s_waitcnt lgkmcnt(1)
	v_mfma_f32_32x32x16_bf16 v[144:159], v[180:183], v[176:179], v[144:159]
	ds_read_b128 v[180:183], v206 offset:32768
	s_waitcnt lgkmcnt(0)
	v_mfma_f32_32x32x16_bf16 v[144:159], v[180:183], v[172:175], v[144:159]
	ds_read_b128 v[180:183], v207 offset:32768
	v_mfma_f32_32x32x16_bf16 v[128:143], v[186:189], v[176:179], v[128:143]
	s_waitcnt lgkmcnt(0)
	v_mfma_f32_32x32x16_bf16 v[144:159], v[180:183], v[168:171], v[144:159]
	v_mfma_f32_32x32x16_bf16 v[128:143], v[190:193], v[172:175], v[128:143]
	s_nop 10
	v_fmamk_f32 v144, v144, 0x3fb8aa3b, v233
	v_fmamk_f32 v145, v145, 0x3fb8aa3b, v233
	v_exp_f32_e32 v144, v144
	v_fmamk_f32 v146, v146, 0x3fb8aa3b, v233
	v_exp_f32_e32 v145, v145
	v_fmamk_f32 v147, v147, 0x3fb8aa3b, v233
	v_exp_f32_e32 v146, v146
	v_fmamk_f32 v148, v148, 0x3fb8aa3b, v233
	v_exp_f32_e32 v147, v147
	v_fmamk_f32 v149, v149, 0x3fb8aa3b, v233
	v_exp_f32_e32 v148, v148
	v_mfma_f32_32x32x16_bf16 v[128:143], v[194:197], v[168:171], v[128:143]
	v_add_f32_e32 v168, 0, v144
	v_fmamk_f32 v150, v150, 0x3fb8aa3b, v233
	v_exp_f32_e32 v149, v149
	v_add_f32_e32 v168, v145, v168
	v_fmamk_f32 v151, v151, 0x3fb8aa3b, v233
	v_exp_f32_e32 v150, v150
	v_add_f32_e32 v168, v146, v168
	v_fmamk_f32 v152, v152, 0x3fb8aa3b, v233
	v_exp_f32_e32 v151, v151
	v_add_f32_e32 v168, v147, v168
	v_exp_f32_e32 v152, v152
	v_fmamk_f32 v153, v153, 0x3fb8aa3b, v233
	v_add_f32_e32 v168, v148, v168
	v_exp_f32_e32 v153, v153
	v_fmamk_f32 v154, v154, 0x3fb8aa3b, v233
	v_add_f32_e32 v168, v149, v168
	v_exp_f32_e32 v154, v154
	v_fmamk_f32 v155, v155, 0x3fb8aa3b, v233
	v_add_f32_e32 v168, v150, v168
	v_exp_f32_e32 v155, v155
	v_fmamk_f32 v156, v156, 0x3fb8aa3b, v233
	v_add_f32_e32 v168, v151, v168
	v_exp_f32_e32 v156, v156
	v_fmamk_f32 v157, v157, 0x3fb8aa3b, v233
	v_add_f32_e32 v168, v152, v168
	v_exp_f32_e32 v157, v157
	v_fmamk_f32 v158, v158, 0x3fb8aa3b, v233
	v_add_f32_e32 v168, v153, v168
	v_exp_f32_e32 v158, v158
	v_fmamk_f32 v159, v159, 0x3fb8aa3b, v233
	v_add_f32_e32 v168, v154, v168
	v_exp_f32_e32 v159, v159
	v_fmamk_f32 v128, v128, 0x3fb8aa3b, v233
	v_add_f32_e32 v168, v155, v168
	v_exp_f32_e32 v128, v128
	v_fmamk_f32 v129, v129, 0x3fb8aa3b, v233
	v_add_f32_e32 v168, v156, v168
	v_exp_f32_e32 v129, v129
	v_fmamk_f32 v130, v130, 0x3fb8aa3b, v233
	v_add_f32_e32 v168, v157, v168
	v_exp_f32_e32 v130, v130
	v_fmamk_f32 v131, v131, 0x3fb8aa3b, v233
	v_add_f32_e32 v168, v158, v168
	v_exp_f32_e32 v131, v131
	v_fmamk_f32 v132, v132, 0x3fb8aa3b, v233
	v_add_f32_e32 v168, v159, v168
	v_exp_f32_e32 v132, v132
	v_fmamk_f32 v133, v133, 0x3fb8aa3b, v233
	v_add_f32_e32 v168, v128, v168
	v_exp_f32_e32 v133, v133
	v_fmamk_f32 v134, v134, 0x3fb8aa3b, v233
	v_add_f32_e32 v168, v129, v168
	v_exp_f32_e32 v134, v134
	v_fmamk_f32 v135, v135, 0x3fb8aa3b, v233
	v_add_f32_e32 v168, v130, v168
	v_exp_f32_e32 v135, v135
	v_fmamk_f32 v136, v136, 0x3fb8aa3b, v233
	v_add_f32_e32 v168, v131, v168
	v_exp_f32_e32 v136, v136
; __device__ __forceinline__ float bf2f(u16 v) { return __uint_as_float(((unsigned)v) << 16); }
; #define MFMA(a, b, c) __builtin_amdgcn_mfma_f32_32x32x16_bf16(a, b, c, 0, 0, 0)
; #define PK4N(PV, BASE, OUT) do { u32x4 w_ = {cvtpk(PV[BASE + 0], PV[BASE + 1]), cvtpk(PV[BASE + 2], PV[BASE + 3]), \
;     cvtpk(PV[BASE + 4], PV[BASE + 5]), cvtpk(PV[BASE + 6], PV[BASE + 7])}; OUT = *reinterpret_cast<bf16x8*>(&w_); } while (0)
; __device__ __forceinline__ void att_qkt(f32x16& p0, f32x16& p1, const char* Kb, const bf16x8 (&qr)[4], int koff, int ksw, int hi) {
;   p0 = f32x16{}; p1 = f32x16{};
; #pragma unroll
;   for (int d0 = 0; d0 < 4; ++d0) {
;     const int co = ((d0 * 2 + hi) ^ ksw) << 4;
;     const bf16x8 b0 = *(const bf16x8*)(Kb + koff + co);
;     const bf16x8 b1 = *(const bf16x8*)(Kb + koff + 4096 + co);
;     p0 = MFMA(b0, qr[d0], p0); p1 = MFMA(b1, qr[d0], p1);
;   }
; }
; __device__ __forceinline__ void sm_fixed(f32x16& p0, f32x16& p1, float mC, float& l_reg, bf16x8& pa0, bf16x8& pa1, bf16x8& pa2, bf16x8& pa3) {
;   constexpr float C = 1.4426950408889634f;
; #pragma unroll
;   for (int r = 0; r < 16; ++r) p0[r] = __builtin_amdgcn_exp2f(fmaf(p0[r], C, -mC));
; #pragma unroll
;   for (int r = 0; r < 16; ++r) p1[r] = __builtin_amdgcn_exp2f(fmaf(p1[r], C, -mC));
;   float ps = 0;
; #pragma unroll
;   for (int r = 0; r < 16; ++r) ps += p0[r];
; #pragma unroll
;   for (int r = 0; r < 16; ++r) ps += p1[r];
;   { auto rr = __builtin_amdgcn_permlane32_swap(__float_as_uint(ps), __float_as_uint(ps), false, false);
;     ps = __uint_as_float(rr[0]) + __uint_as_float(rr[1]); }
;   l_reg += ps;
;     ...
;   PK4N(p0, 0, pa0); PK4N(p0, 8, pa1); PK4N(p1, 0, pa2); PK4N(p1, 8, pa3);
;     ...
; }
; #pragma unroll
;   for (int q = 0; q < 8; ++q) { const float f = bf2f((u16)v[q]); s += f * f; } return s; }
; __device__ __forceinline__ void att_qkt_p(f32x16& p0, f32x16& p1, const char* Kb, const bf16x8 (&qr)[2], const char* Qp, int koff, int ksw, int hi) {
;   p0 = f32x16{}; p1 = f32x16{};
; #pragma unroll
;   for (int d0 = 0; d0 < 4; ++d0) {
;     const int co = ((d0 * 2 + hi) ^ ksw) << 4;
;     const bf16x8 b0 = *(const bf16x8*)(Kb + koff + co);
;     const bf16x8 b1 = *(const bf16x8*)(Kb + koff + 4096 + co);
;     const bf16x8 qd = d0 < 2 ? qr[d0 & 1] : *(const bf16x8*)(Qp + (d0 - 2) * 4096);
;     p0 = MFMA(b0, qd, p0); p1 = MFMA(b1, qd, p1);
;   }
; }
	v_fmamk_f32 v137, v137, 0x3fb8aa3b, v233
	v_add_f32_e32 v168, v132, v168
	v_exp_f32_e32 v137, v137
	v_fmamk_f32 v138, v138, 0x3fb8aa3b, v233
	v_add_f32_e32 v168, v133, v168
	v_exp_f32_e32 v138, v138
	v_fmamk_f32 v139, v139, 0x3fb8aa3b, v233
	v_add_f32_e32 v168, v134, v168
	v_exp_f32_e32 v139, v139
	v_fmamk_f32 v140, v140, 0x3fb8aa3b, v233
	v_add_f32_e32 v168, v135, v168
	v_exp_f32_e32 v140, v140
	v_fmamk_f32 v141, v141, 0x3fb8aa3b, v233
	v_add_f32_e32 v168, v136, v168
	v_exp_f32_e32 v141, v141
	v_fmamk_f32 v142, v142, 0x3fb8aa3b, v233
	v_add_f32_e32 v168, v137, v168
	v_exp_f32_e32 v142, v142
	v_fmac_f32_e32 v233, 0x3fb8aa3b, v143
	v_add_f32_e32 v168, v138, v168
	v_exp_f32_e32 v143, v233
	v_add_f32_e32 v168, v139, v168
	v_add_f32_e32 v168, v140, v168
	v_add_f32_e32 v168, v141, v168
	v_add_f32_e32 v168, v142, v168
	v_add_f32_e32 v186, v143, v168
	v_mov_b32_e32 v187, v186
	s_nop 1
	v_permlane32_swap_b32_e32 v186, v187
	v_cvt_pk_bf16_f32 v176, v144, v145
	v_cvt_pk_bf16_f32 v177, v146, v147
	v_cvt_pk_bf16_f32 v178, v148, v149
	v_cvt_pk_bf16_f32 v179, v150, v151
	v_cvt_pk_bf16_f32 v180, v152, v153
	v_cvt_pk_bf16_f32 v181, v154, v155
	v_cvt_pk_bf16_f32 v182, v156, v157
	v_cvt_pk_bf16_f32 v183, v158, v159
	v_cvt_pk_bf16_f32 v168, v128, v129
	v_cvt_pk_bf16_f32 v169, v130, v131
	v_cvt_pk_bf16_f32 v170, v132, v133
	v_cvt_pk_bf16_f32 v171, v134, v135
	v_cvt_pk_bf16_f32 v172, v136, v137
	v_cvt_pk_bf16_f32 v173, v138, v139
	v_cvt_pk_bf16_f32 v174, v140, v141
	v_cvt_pk_bf16_f32 v175, v142, v143
	ds_read_b128 v[128:131], v198 offset:40960
	ds_read_b128 v[132:135], v198 offset:45056
	s_waitcnt lgkmcnt(1)
	v_mfma_f32_32x32x16_bf16 v[144:159], v[128:131], v[164:167], 0
	s_waitcnt lgkmcnt(0)
	v_mfma_f32_32x32x16_bf16 v[128:143], v[132:135], v[164:167], 0
	ds_read_b128 v[164:167], v199 offset:40960
	ds_read_b128 v[188:191], v199 offset:45056
	s_waitcnt lgkmcnt(0)
	v_mfma_f32_32x32x16_bf16 v[128:143], v[188:191], v[160:163], v[128:143]
	v_mfma_f32_32x32x16_bf16 v[144:159], v[164:167], v[160:163], v[144:159]
	ds_read_b128 v[160:163], v206 offset:40960
	ds_read_b128 v[164:167], v206 offset:45056
	ds_read_b128 v[188:191], v230
	s_waitcnt lgkmcnt(0)
	v_mfma_f32_32x32x16_bf16 v[128:143], v[164:167], v[188:191], v[128:143]
	v_mfma_f32_32x32x16_bf16 v[144:159], v[160:163], v[188:191], v[144:159]
	ds_read_b128 v[160:163], v207 offset:40960
	ds_read_b128 v[164:167], v207 offset:45056
	ds_read_b128 v[188:191], v230 offset:4096
	s_waitcnt lgkmcnt(0)
	v_mfma_f32_32x32x16_bf16 v[128:143], v[164:167], v[188:191], v[128:143]
	v_mfma_f32_32x32x16_bf16 v[144:159], v[160:163], v[188:191], v[144:159]
	s_nop 10
	v_fmamk_f32 v128, v128, 0x3fb8aa3b, v231
	v_exp_f32_e32 v162, v128
	v_fmamk_f32 v128, v129, 0x3fb8aa3b, v231
	v_exp_f32_e32 v163, v128
	v_fmamk_f32 v128, v130, 0x3fb8aa3b, v231
	v_exp_f32_e32 v164, v128
	v_fmamk_f32 v128, v131, 0x3fb8aa3b, v231
	v_exp_f32_e32 v165, v128
	v_fmamk_f32 v128, v132, 0x3fb8aa3b, v231
	v_exp_f32_e32 v166, v128
	v_fmamk_f32 v128, v133, 0x3fb8aa3b, v231
	v_exp_f32_e32 v167, v128
	v_fmamk_f32 v128, v134, 0x3fb8aa3b, v231
	v_exp_f32_e32 v188, v128
	v_fmamk_f32 v128, v135, 0x3fb8aa3b, v231
	v_exp_f32_e32 v189, v128
	v_fmamk_f32 v128, v136, 0x3fb8aa3b, v231
	v_exp_f32_e32 v190, v128
	v_fmamk_f32 v128, v137, 0x3fb8aa3b, v231
	v_fmamk_f32 v144, v144, 0x3fb8aa3b, v231
	v_exp_f32_e32 v191, v128
	v_fmamk_f32 v128, v138, 0x3fb8aa3b, v231
	v_exp_f32_e32 v160, v144
	v_fmamk_f32 v144, v145, 0x3fb8aa3b, v231
	v_exp_f32_e32 v192, v128
	v_fmamk_f32 v128, v139, 0x3fb8aa3b, v231
	v_exp_f32_e32 v145, v144
	v_fmamk_f32 v144, v146, 0x3fb8aa3b, v231
	v_exp_f32_e32 v193, v128
	v_fmamk_f32 v128, v140, 0x3fb8aa3b, v231
	v_exp_f32_e32 v161, v144
	v_fmamk_f32 v144, v147, 0x3fb8aa3b, v231
	v_exp_f32_e32 v194, v128
	v_fmamk_f32 v128, v141, 0x3fb8aa3b, v231
	v_exp_f32_e32 v147, v144
	v_fmamk_f32 v144, v148, 0x3fb8aa3b, v231
	v_exp_f32_e32 v195, v128
	v_fmamk_f32 v128, v142, 0x3fb8aa3b, v231
	v_exp_f32_e32 v148, v144
	v_fmamk_f32 v144, v149, 0x3fb8aa3b, v231
	v_exp_f32_e32 v196, v128
	v_add_f32_e32 v128, 0, v160
	v_exp_f32_e32 v149, v144
	v_fmamk_f32 v144, v150, 0x3fb8aa3b, v231
	v_add_f32_e32 v128, v145, v128
	v_exp_f32_e32 v150, v144
	v_fmamk_f32 v144, v151, 0x3fb8aa3b, v231
	v_add_f32_e32 v128, v161, v128
	v_exp_f32_e32 v151, v144
	v_fmamk_f32 v144, v152, 0x3fb8aa3b, v231
	v_add_f32_e32 v128, v147, v128
	v_exp_f32_e32 v152, v144
	v_fmamk_f32 v144, v153, 0x3fb8aa3b, v231
	v_add_f32_e32 v128, v148, v128
	v_exp_f32_e32 v153, v144
	v_fmamk_f32 v144, v154, 0x3fb8aa3b, v231
	v_add_f32_e32 v128, v149, v128
	v_exp_f32_e32 v154, v144
	v_fmamk_f32 v144, v155, 0x3fb8aa3b, v231
	v_add_f32_e32 v128, v150, v128
	v_exp_f32_e32 v155, v144
	v_fmamk_f32 v144, v156, 0x3fb8aa3b, v231
	v_add_f32_e32 v128, v151, v128
	v_exp_f32_e32 v156, v144
	v_fmamk_f32 v144, v157, 0x3fb8aa3b, v231
	v_add_f32_e32 v128, v152, v128
	v_exp_f32_e32 v157, v144
	v_fmamk_f32 v144, v158, 0x3fb8aa3b, v231
	v_add_f32_e32 v128, v153, v128
	v_exp_f32_e32 v158, v144
	v_fmamk_f32 v144, v159, 0x3fb8aa3b, v231
	v_add_f32_e32 v128, v154, v128
	v_exp_f32_e32 v159, v144
	v_add_f32_e32 v128, v155, v128
	v_add_f32_e32 v128, v156, v128
	v_add_f32_e32 v128, v157, v128
	v_add_f32_e32 v128, v158, v128
	v_add_f32_e32 v128, v159, v128
	v_add_f32_e32 v128, v162, v128
	v_add_f32_e32 v128, v163, v128
	v_add_f32_e32 v128, v164, v128
	v_add_f32_e32 v128, v165, v128
	v_add_f32_e32 v128, v166, v128
	v_add_f32_e32 v128, v167, v128
	v_add_f32_e32 v128, v188, v128
	v_add_f32_e32 v128, v189, v128
	v_add_f32_e32 v128, v190, v128
	v_add_f32_e32 v128, v191, v128
	v_fmac_f32_e32 v231, 0x3fb8aa3b, v143
	v_add_f32_e32 v128, v192, v128
	v_exp_f32_e32 v143, v231
	v_add_f32_e32 v128, v193, v128
	v_add_f32_e32 v128, v194, v128
	v_add_f32_e32 v128, v195, v128
	v_add_f32_e32 v128, v196, v128
	v_add_f32_e32 v144, v143, v128
	v_mov_b32_e32 v146, v144
	s_nop 1
	v_permlane32_swap_b32_e32 v144, v146
	v_cvt_pk_bf16_f32 v128, v160, v145
	v_cvt_pk_bf16_f32 v129, v161, v147
	v_cvt_pk_bf16_f32 v130, v148, v149
	v_cvt_pk_bf16_f32 v131, v150, v151
	v_cvt_pk_bf16_f32 v132, v152, v153
	v_cvt_pk_bf16_f32 v133, v154, v155
	v_cvt_pk_bf16_f32 v134, v156, v157
	v_cvt_pk_bf16_f32 v135, v158, v159
	v_cvt_pk_bf16_f32 v136, v162, v163
	v_cvt_pk_bf16_f32 v137, v164, v165
	v_cvt_pk_bf16_f32 v138, v166, v167
	v_cvt_pk_bf16_f32 v139, v188, v189
	v_cvt_pk_bf16_f32 v140, v190, v191
	v_cvt_pk_bf16_f32 v141, v192, v193
	v_cvt_pk_bf16_f32 v142, v194, v195
	v_cvt_pk_bf16_f32 v143, v196, v143
	ds_read_b64_tr_b16 v[148:149], v185 offset:0
	ds_read_b64_tr_b16 v[150:151], v185 offset:0x800
	ds_read_b64_tr_b16 v[152:153], v185 offset:0x1000
	ds_read_b64_tr_b16 v[154:155], v185 offset:0x1800
	s_waitcnt lgkmcnt(0)
; __device__ __forceinline__ int crow(int r, int hi) { return (r & 3) + 8 * (r >> 2) + 4 * hi; }
; #define SBAR() __builtin_amdgcn_sched_barrier(0)
; #define MFMA(a, b, c) __builtin_amdgcn_mfma_f32_32x32x16_bf16(a, b, c, 0, 0, 0)
; template <int D0> __device__ __forceinline__ void pv_two(f32x16& oa, f32x16& ob, int vb, bf16x8 a0, bf16x8 a1, bf16x8 a2, bf16x8 a3,
;                                                          bf16x8 b0, bf16x8 b1, bf16x8 b2, bf16x8 b3) {
;     ...
;   { const s16x4 l0 = tr_read<v_rd_off(D0, 0, 0)>(vb), h0 = tr_read<v_rd_off(D0, 0, 1)>(vb), l1 = tr_read<v_rd_off(D0, 1, 0)>(vb), h1 = tr_read<v_rd_off(D0, 1, 1)>(vb);
;     asm volatile("s_waitcnt lgkmcnt(0)" ::: "memory"); SBAR();
;     const bf16x8 v0 = PKV(l0, h0), v1 = PKV(l1, h1);
;     oa = MFMA(a0, v0, oa); ob = MFMA(b0, v0, ob); oa = MFMA(a1, v1, oa); ob = MFMA(b1, v1, ob); }
;   { const s16x4 l2 = tr_read<v_rd_off(D0, 2, 0)>(vb), h2 = tr_read<v_rd_off(D0, 2, 1)>(vb), l3 = tr_read<v_rd_off(D0, 3, 0)>(vb), h3 = tr_read<v_rd_off(D0, 3, 1)>(vb);
;     asm volatile("s_waitcnt lgkmcnt(0)" ::: "memory"); SBAR();
;     const bf16x8 v2 = PKV(l2, h2), v3 = PKV(l3, h3);
;     oa = MFMA(a2, v2, oa); ob = MFMA(b2, v2, ob); oa = MFMA(a3, v3, oa); ob = MFMA(b3, v3, ob); }
;     ...
; }
; __device__ __forceinline__ void attn_item(const P& p, int layer, int item, char* lds) {
;     ...
;   float r1[16], r2[16];
;   if (hi == 0) li_l[r32] = l1;
;   asm volatile("s_waitcnt lgkmcnt(0)" ::: "memory");
; #pragma unroll
;   for (int r = 0; r < 16; ++r) r1[r] = 1.f / li_l[crow(r, hi)];
;   asm volatile("s_waitcnt lgkmcnt(0)" ::: "memory");
;   if (hi == 0) li_l[r32] = l2;
;   asm volatile("s_waitcnt lgkmcnt(0)" ::: "memory");
; #pragma unroll
;   for (int r = 0; r < 16; ++r) r2[r] = lam / li_l[crow(r, hi)];
	s_nop 0
	v_mfma_f32_32x32x16_bf16 v[64:79], v[176:179], v[148:151], v[64:79]
	v_mfma_f32_32x32x16_bf16 v[0:15], v[128:131], v[148:151], v[0:15]
	ds_read_b64_tr_b16 v[148:149], v185 offset:0x2000
	ds_read_b64_tr_b16 v[150:151], v185 offset:0x2800
	v_mfma_f32_32x32x16_bf16 v[64:79], v[180:183], v[152:155], v[64:79]
	v_mfma_f32_32x32x16_bf16 v[0:15], v[132:135], v[152:155], v[0:15]
	ds_read_b64_tr_b16 v[152:153], v185 offset:0x3000
	ds_read_b64_tr_b16 v[154:155], v185 offset:0x3800
	s_waitcnt lgkmcnt(0)
	v_mfma_f32_32x32x16_bf16 v[64:79], v[168:171], v[148:151], v[64:79]
	v_mfma_f32_32x32x16_bf16 v[0:15], v[136:139], v[148:151], v[0:15]
	ds_read_b64_tr_b16 v[148:149], v185 offset:0x200
	ds_read_b64_tr_b16 v[150:151], v185 offset:0xa00
	v_mfma_f32_32x32x16_bf16 v[64:79], v[172:175], v[152:155], v[64:79]
	v_mfma_f32_32x32x16_bf16 v[0:15], v[140:143], v[152:155], v[0:15]
	ds_read_b64_tr_b16 v[152:153], v185 offset:0x1200
	ds_read_b64_tr_b16 v[154:155], v185 offset:0x1a00
	s_waitcnt lgkmcnt(0)
	v_mfma_f32_32x32x16_bf16 v[80:95], v[176:179], v[148:151], v[80:95]
	v_mfma_f32_32x32x16_bf16 v[16:31], v[128:131], v[148:151], v[16:31]
	ds_read_b64_tr_b16 v[148:149], v185 offset:0x2200
	ds_read_b64_tr_b16 v[150:151], v185 offset:0x2a00
	v_mfma_f32_32x32x16_bf16 v[80:95], v[180:183], v[152:155], v[80:95]
	v_mfma_f32_32x32x16_bf16 v[16:31], v[132:135], v[152:155], v[16:31]
	ds_read_b64_tr_b16 v[152:153], v185 offset:0x3200
	ds_read_b64_tr_b16 v[154:155], v185 offset:0x3a00
	s_waitcnt lgkmcnt(0)
	v_mfma_f32_32x32x16_bf16 v[80:95], v[168:171], v[148:151], v[80:95]
	v_mfma_f32_32x32x16_bf16 v[16:31], v[136:139], v[148:151], v[16:31]
	ds_read_b64_tr_b16 v[148:149], v185 offset:0x400
	ds_read_b64_tr_b16 v[150:151], v185 offset:0xc00
	v_mfma_f32_32x32x16_bf16 v[80:95], v[172:175], v[152:155], v[80:95]
	v_mfma_f32_32x32x16_bf16 v[16:31], v[140:143], v[152:155], v[16:31]
	ds_read_b64_tr_b16 v[152:153], v185 offset:0x1400
	ds_read_b64_tr_b16 v[154:155], v185 offset:0x1c00
	s_waitcnt lgkmcnt(0)
	v_mfma_f32_32x32x16_bf16 v[96:111], v[176:179], v[148:151], v[96:111]
	v_mfma_f32_32x32x16_bf16 v[32:47], v[128:131], v[148:151], v[32:47]
	ds_read_b64_tr_b16 v[148:149], v185 offset:0x2400
	ds_read_b64_tr_b16 v[150:151], v185 offset:0x2c00
	v_mfma_f32_32x32x16_bf16 v[96:111], v[180:183], v[152:155], v[96:111]
	v_mfma_f32_32x32x16_bf16 v[32:47], v[132:135], v[152:155], v[32:47]
	ds_read_b64_tr_b16 v[152:153], v185 offset:0x3400
	ds_read_b64_tr_b16 v[154:155], v185 offset:0x3c00
	s_waitcnt lgkmcnt(0)
	v_mfma_f32_32x32x16_bf16 v[96:111], v[168:171], v[148:151], v[96:111]
	v_mfma_f32_32x32x16_bf16 v[32:47], v[136:139], v[148:151], v[32:47]
	ds_read_b64_tr_b16 v[148:149], v185 offset:0x600
	ds_read_b64_tr_b16 v[150:151], v185 offset:0xe00
	v_mfma_f32_32x32x16_bf16 v[96:111], v[172:175], v[152:155], v[96:111]
	v_mfma_f32_32x32x16_bf16 v[32:47], v[140:143], v[152:155], v[32:47]
	ds_read_b64_tr_b16 v[152:153], v185 offset:0x1600
	ds_read_b64_tr_b16 v[154:155], v185 offset:0x1e00
	s_waitcnt lgkmcnt(0)
	v_mfma_f32_32x32x16_bf16 v[112:127], v[176:179], v[148:151], v[112:127]
	v_mfma_f32_32x32x16_bf16 v[48:63], v[128:131], v[148:151], v[48:63]
	ds_read_b64_tr_b16 v[128:129], v185 offset:0x2600
	ds_read_b64_tr_b16 v[130:131], v185 offset:0x2e00
	ds_read_b64_tr_b16 v[148:149], v185 offset:0x3600
	ds_read_b64_tr_b16 v[150:151], v185 offset:0x3e00
	s_waitcnt lgkmcnt(0)
	v_mfma_f32_32x32x16_bf16 v[112:127], v[180:183], v[152:155], v[112:127]
	v_mfma_f32_32x32x16_bf16 v[48:63], v[132:135], v[152:155], v[48:63]
	v_mfma_f32_32x32x16_bf16 v[112:127], v[168:171], v[128:131], v[112:127]
	v_cmp_gt_u32_e32 vcc, 32, v228
	v_lshl_add_u32 v147, v226, 2, v184
	v_mfma_f32_32x32x16_bf16 v[48:63], v[136:139], v[128:131], v[48:63]
	v_mfma_f32_32x32x16_bf16 v[112:127], v[172:175], v[148:151], v[112:127]
	v_mfma_f32_32x32x16_bf16 v[48:63], v[140:143], v[148:151], v[48:63]
	s_and_saveexec_b64 s[6:7], vcc
	v_add_f32_e32 v128, v186, v187
	v_add_f32_e32 v128, v204, v128
	ds_write_b32 v147, v128
	s_or_b64 exec, exec, s[6:7]
	s_waitcnt lgkmcnt(0)
	v_add_u32_e32 v145, v184, v200
	ds_read_b128 v[128:131], v145
	ds_read_b128 v[132:135], v145 offset:32
	ds_read_b128 v[136:139], v145 offset:64
	ds_read_b128 v[140:143], v145 offset:96
	s_waitcnt lgkmcnt(0)
	s_mov_b64 s[6:7], exec
	s_and_b64 s[18:19], s[6:7], vcc
	v_mov_b32_e32 v206, 0x14000
	v_mov_b32_e32 v207, 0x68000
	v_mov_b32_e32 v208, 0x16000
	v_mov_b32_e32 v209, 0x66000
	v_mov_b32_e32 v210, 0x18000
	v_mov_b32_e32 v211, 0x64000
	v_mov_b32_e32 v212, 0x1a000
	v_mov_b32_e32 v213, 0x62000
	v_mov_b32_e32 v214, 0x1c000
	v_mov_b32_e32 v216, 0x60000
	v_mov_b32_e32 v218, 0x1e000
	v_mov_b32_e32 v219, 0x5e000
	v_mov_b32_e32 v220, 0x20000
	v_mov_b32_e32 v221, 0x5c000
	v_mov_b32_e32 v228, 0x22000
	v_mov_b32_e32 v230, 0x5a000
	v_mov_b32_e32 v231, 0x24000
	v_mov_b32_e32 v232, 0x58000
	v_mov_b32_e32 v233, 0x26000
	v_mov_b32_e32 v234, 0x56000
	v_mov_b32_e32 v235, 0x28000
	v_mov_b32_e32 v236, 0x54000
	v_mov_b32_e32 v237, 0x2a000
	v_mov_b32_e32 v238, 0x52000
	v_mov_b32_e32 v239, 0x2c000
	v_mov_b32_e32 v240, 0x50000
	v_mov_b32_e32 v241, 0x2e000
	v_mov_b32_e32 v242, 0x4e000
	v_mov_b32_e32 v243, 0x30000
	v_mov_b32_e32 v244, 0x4c000
	v_mov_b32_e32 v245, 0x32000
	v_mov_b32_e32 v246, 0x4a000
	v_mov_b32_e32 v247, 0x34000
	v_mov_b32_e32 v248, 0x48000
	v_mov_b32_e32 v249, 0x36000
	v_mov_b32_e32 v179, 0x46000
	v_mov_b32_e32 v181, 0x38000
	s_mov_b64 exec, s[18:19]
	s_cbranch_execz .LBB0_270
	v_add_f32_e32 v144, v144, v146
	v_add_f32_e32 v144, v205, v144
	ds_write_b32 v147, v144
	s_branch .LBB0_270
